# in-projection GEMM epilogue: nontemporal hint on the 56 bf16 activation stores (they no longer evict the K-loop A/B tiles from L2)
# speedup vs baseline: 1.0157x; 1.0059x over previous
; __device__ __forceinline__ f32x4 silu4(const f32x4 z) { f32x4 r; r[0] = z[0] * fast_sigmoid(z[0]); r[1] = z[1] * fast_sigmoid(z[1]); r[2] = z[2] * fast_sigmoid(z[2]); r[3] = z[3] * fast_sigmoid(z[3]); return r; }
; __device__ __forceinline__ f32x4 sigm4(const f32x4 z) { f32x4 r; r[0] = fast_sigmoid(z[0]); r[1] = fast_sigmoid(z[1]); r[2] = fast_sigmoid(z[2]); r[3] = fast_sigmoid(z[3]); return r; }
; __device__ __forceinline__ u32x2 pk4(const f32x4 v) { u32x2 w; w.x = pk2(v[0], v[1]); w.y = pk2(v[2], v[3]); return w; }
;     __device__ __forceinline__ void operator()(const AccT& acc, const Unit& u, int wr, int wc, int fr, int fq) const {
;     ...
;                     const int row = row0 + ai * 128 + m * 16;
;                     float* vo = (row < MP ? vp + (size_t)row * DM : vs + (size_t)(row - MP) * DM) + colt;
;                     const bool vok = (grp == 0) && (row < MV);
; #pragma unroll
;                     for (int bj = 0; bj < 2; ++bj) {
;                         f32x4 v0 = acc[ai][bj][m][0], v1 = acc[ai][bj][m][1];
;                         if (vok) { __builtin_nontemporal_store(v0, (f32x4*)(vo + bj * 128)); __builtin_nontemporal_store(v1, (f32x4*)(vo + bj * 128 + 4)); }
;                         if (grp == 1) { v0 = silu4(v0); v1 = silu4(v1); } else if (grp >= 2) { v0 = sigm4(v0); v1 = sigm4(v1); }
;                         const u32x2 p0 = pk4(v0), p1 = pk4(v1); const u32x4 pw = {p0.x, p0.y, p1.x, p1.y};
;                         *(u32x4*)(O + (size_t)row * DM + bj * 128) = pw;
.LBB0_732:
	s_add_i32 s8, s8, 4
	s_mul_hi_u32 s25, s8, 0x4100000
	s_mul_i32 s8, s8, 0x4100000
	v_readlane_b32 s26, v254, 55
	v_readlane_b32 s27, v254, 56
	s_add_u32 s24, s26, s8
	s_addc_u32 s25, s27, s25
	v_lshlrev_b32_e32 v144, 1, v148
	v_mov_b32_e32 v145, v181
	v_lshl_add_u64 v[144:145], s[24:25], 0, v[144:145]
	v_lshlrev_b64 v[148:149], 11, v[170:171]
	v_lshl_add_u64 v[148:149], v[144:145], 0, v[148:149]
	v_cvt_pk_bf16_f32 v150, v150, v151
	v_cvt_pk_bf16_f32 v151, v152, v153
	v_cvt_pk_bf16_f32 v152, v154, v155
	v_cvt_pk_bf16_f32 v153, v172, v173
	global_store_dwordx4 v[148:149], v[150:153], off nt
	s_and_saveexec_b64 s[24:25], s[20:21]
	s_cbranch_execz .LBB0_734
	global_store_dwordx4 v[146:147], v[136:139], off offset:512 nt
	global_store_dwordx4 v[146:147], v[128:131], off offset:528 nt

; __device__ __forceinline__ f32x4 silu4(const f32x4 z) { f32x4 r; r[0] = z[0] * fast_sigmoid(z[0]); r[1] = z[1] * fast_sigmoid(z[1]); r[2] = z[2] * fast_sigmoid(z[2]); r[3] = z[3] * fast_sigmoid(z[3]); return r; }
; __device__ __forceinline__ f32x4 sigm4(const f32x4 z) { f32x4 r; r[0] = fast_sigmoid(z[0]); r[1] = fast_sigmoid(z[1]); r[2] = fast_sigmoid(z[2]); r[3] = fast_sigmoid(z[3]); return r; }
; __device__ __forceinline__ u32x2 pk4(const f32x4 v) { u32x2 w; w.x = pk2(v[0], v[1]); w.y = pk2(v[2], v[3]); return w; }
;     __device__ __forceinline__ void operator()(const AccT& acc, const Unit& u, int wr, int wc, int fr, int fq) const {
;     ...
;                     float* vo = (row < MP ? vp + (size_t)row * DM : vs + (size_t)(row - MP) * DM) + colt;
;     ...
;                     for (int bj = 0; bj < 2; ++bj) {
;                         f32x4 v0 = acc[ai][bj][m][0], v1 = acc[ai][bj][m][1];
;                         if (vok) { __builtin_nontemporal_store(v0, (f32x4*)(vo + bj * 128)); __builtin_nontemporal_store(v1, (f32x4*)(vo + bj * 128 + 4)); }
;                         if (grp == 1) { v0 = silu4(v0); v1 = silu4(v1); } else if (grp >= 2) { v0 = sigm4(v0); v1 = sigm4(v1); }
;                         const u32x2 p0 = pk4(v0), p1 = pk4(v1); const u32x4 pw = {p0.x, p0.y, p1.x, p1.y};
;                         *(u32x4*)(O + (size_t)row * DM + bj * 128) = pw;
.LBB0_740:
	v_cvt_pk_bf16_f32 v172, v146, v147
	v_or_b32_e32 v146, 16, v170
	v_cmp_lt_i32_e32 vcc, s93, v146
	v_cvt_pk_bf16_f32 v173, v150, v151
	v_cvt_pk_bf16_f32 v174, v152, v153
	v_cvt_pk_bf16_f32 v175, v154, v155
	global_store_dwordx4 v[148:149], v[172:175], off offset:256 nt
	s_and_saveexec_b64 s[20:21], vcc
	s_xor_b64 s[20:21], exec, s[20:21]
	s_cbranch_execz .LBB0_742
	v_add_u32_e32 v148, 0xffff7fd0, v170
	v_mov_b32_e32 v149, v181
	v_readlane_b32 s22, v252, 38
	v_lshlrev_b64 v[148:149], 12, v[148:149]
	v_readlane_b32 s23, v252, 39
	v_mov_b32_e32 v147, v181
	s_nop 0
	v_lshl_add_u64 v[148:149], s[22:23], 0, v[148:149]

; __device__ __forceinline__ float fast_sigmoid(float x) { return __builtin_amdgcn_rcpf(1.f + __expf(-x)); }
; __device__ __forceinline__ u32x2 pk4(const f32x4 v) { u32x2 w; w.x = pk2(v[0], v[1]); w.y = pk2(v[2], v[3]); return w; }
; __device__ __forceinline__ f32x4 silu4(const f32x4 z) { f32x4 r; r[0] = z[0] * fast_sigmoid(z[0]); r[1] = z[1] * fast_sigmoid(z[1]); r[2] = z[2] * fast_sigmoid(z[2]); r[3] = z[3] * fast_sigmoid(z[3]); return r; }
;     __device__ __forceinline__ void operator()(const AccT& acc, const Unit& u, int wr, int wc, int fr, int fq) const {
;     ...
;             const int ch0 = 128 * (pn & 7) + 32 * wc + 8 * fq;
;             bf16_t* O = PA + (ch_tile ? (size_t)0 : (size_t)MPAD * DM) + ch0;
; #pragma unroll
;             for (int ai = 0; ai < 2; ++ai)
; #pragma unroll
;                 for (int m = 0; m < 4; ++m) {
;                     const int row = row0 + ai * 128 + m * 16;
;                     f32x4 o[2];
; #pragma unroll
;                     for (int n = 0; n < 2; ++n) { const f32x4 p0 = acc[ai][0][m][n], p1 = acc[ai][1][m][n]; o[n] = ch_tile ? p0 * p1 : silu4(p1) * p0; }
;                     const u32x2 w0 = pk4(o[0]), w1 = pk4(o[1]); const u32x4 pw = {w0.x, w0.y, w1.x, w1.y};
;                     *(u32x4*)(O + (size_t)row * DM) = pw;
;                 }
.LBB0_755:
	s_lshl_b32 s8, s58, 7
	s_and_b32 s8, s8, 0x380
	s_and_b64 s[0:1], exec, s[0:1]
	s_cselect_b32 s0, 0, 0x4100000
	v_readlane_b32 s20, v254, 55
	v_pk_mul_f32 v[140:141], v[140:141], v[136:137]
	v_or_b32_e32 v136, s8, v202
	v_readlane_b32 s21, v254, 56
	s_add_u32 s0, s20, s0
	s_addc_u32 s1, s21, 0
	v_lshlrev_b32_e32 v180, 1, v136
	v_ashrrev_i32_e32 v171, 31, v170
	v_lshl_add_u64 v[136:137], s[0:1], 0, v[180:181]
	v_pk_mul_f32 v[134:135], v[134:135], v[130:131]
	v_pk_mul_f32 v[130:131], v[132:133], v[128:129]
	v_lshlrev_b64 v[132:133], 11, v[170:171]
	v_lshl_add_u64 v[132:133], v[136:137], 0, v[132:133]
	s_and_b64 vcc, exec, s[40:41]
	v_pk_mul_f32 v[138:139], v[142:143], v[138:139]
	v_cvt_pk_bf16_f32 v128, v140, v141
	v_cvt_pk_bf16_f32 v130, v130, v131
	v_cvt_pk_bf16_f32 v131, v134, v135
	s_nop 0
	v_cvt_pk_bf16_f32 v129, v138, v139
	global_store_dwordx4 v[132:133], v[128:131], off nt
	s_cbranch_vccnz .LBB0_757
	s_nop 0
	v_mul_f32_e32 v128, 0xbfb8aa3b, v120
	v_mul_f32_e32 v129, 0xbfb8aa3b, v121
	v_mul_f32_e32 v130, 0xbfb8aa3b, v122
	v_mul_f32_e32 v131, 0xbfb8aa3b, v123
	v_exp_f32_e32 v128, v128
	v_exp_f32_e32 v129, v129
	v_exp_f32_e32 v130, v130
	v_exp_f32_e32 v131, v131
	v_add_f32_e32 v128, 1.0, v128
	v_add_f32_e32 v129, 1.0, v129
	v_add_f32_e32 v130, 1.0, v130
	v_add_f32_e32 v131, 1.0, v131
	v_rcp_f32_e32 v128, v128
	v_rcp_f32_e32 v130, v130
	v_rcp_f32_e32 v131, v131
	v_rcp_f32_e32 v129, v129
	v_pk_mul_f32 v[122:123], v[122:123], v[130:131]
	v_pk_mul_f32 v[120:121], v[120:121], v[128:129]

; __device__ __forceinline__ float fast_sigmoid(float x) { return __builtin_amdgcn_rcpf(1.f + __expf(-x)); }
; __device__ __forceinline__ u32x2 pk4(const f32x4 v) { u32x2 w; w.x = pk2(v[0], v[1]); w.y = pk2(v[2], v[3]); return w; }
; __device__ __forceinline__ f32x4 silu4(const f32x4 z) { f32x4 r; r[0] = z[0] * fast_sigmoid(z[0]); r[1] = z[1] * fast_sigmoid(z[1]); r[2] = z[2] * fast_sigmoid(z[2]); r[3] = z[3] * fast_sigmoid(z[3]); return r; }
;     __device__ __forceinline__ void operator()(const AccT& acc, const Unit& u, int wr, int wc, int fr, int fq) const {
;     ...
;                 for (int m = 0; m < 4; ++m) {
;                     const int row = row0 + ai * 128 + m * 16;
;                     f32x4 o[2];
; #pragma unroll
;                     for (int n = 0; n < 2; ++n) { const f32x4 p0 = acc[ai][0][m][n], p1 = acc[ai][1][m][n]; o[n] = ch_tile ? p0 * p1 : silu4(p1) * p0; }
;                     const u32x2 w0 = pk4(o[0]), w1 = pk4(o[1]); const u32x4 pw = {w0.x, w0.y, w1.x, w1.y};
;                     *(u32x4*)(O + (size_t)row * DM) = pw;
;                 }
.LBB0_759:
	v_pk_mul_f32 v[118:119], v[118:119], v[114:115]
	v_pk_mul_f32 v[114:115], v[116:117], v[112:113]
	v_or_b32_e32 v116, 16, v170
	v_ashrrev_i32_e32 v117, 31, v116
	v_lshlrev_b64 v[116:117], 11, v[116:117]
	v_lshl_add_u64 v[116:117], v[136:137], 0, v[116:117]
	s_and_b64 vcc, exec, s[40:41]
	v_pk_mul_f32 v[122:123], v[126:127], v[122:123]
	v_pk_mul_f32 v[120:121], v[124:125], v[120:121]
	v_cvt_pk_bf16_f32 v113, v122, v123
	v_cvt_pk_bf16_f32 v114, v114, v115
	v_cvt_pk_bf16_f32 v115, v118, v119
	s_nop 0
	v_cvt_pk_bf16_f32 v112, v120, v121
	global_store_dwordx4 v[116:117], v[112:115], off nt
	s_cbranch_vccnz .LBB0_761
	s_nop 0
	v_mul_f32_e32 v112, 0xbfb8aa3b, v104
	v_mul_f32_e32 v113, 0xbfb8aa3b, v105
	v_mul_f32_e32 v114, 0xbfb8aa3b, v106
	v_mul_f32_e32 v115, 0xbfb8aa3b, v107
	v_exp_f32_e32 v112, v112
	v_exp_f32_e32 v113, v113
	v_exp_f32_e32 v114, v114
	v_exp_f32_e32 v115, v115
	v_add_f32_e32 v112, 1.0, v112
	v_add_f32_e32 v113, 1.0, v113
	v_add_f32_e32 v114, 1.0, v114
	v_add_f32_e32 v115, 1.0, v115
	v_rcp_f32_e32 v112, v112
	v_rcp_f32_e32 v114, v114
	v_rcp_f32_e32 v115, v115
	v_rcp_f32_e32 v113, v113
	v_pk_mul_f32 v[106:107], v[106:107], v[114:115]
	v_pk_mul_f32 v[104:105], v[104:105], v[112:113]

; __device__ __forceinline__ float fast_sigmoid(float x) { return __builtin_amdgcn_rcpf(1.f + __expf(-x)); }
; __device__ __forceinline__ u32x2 pk4(const f32x4 v) { u32x2 w; w.x = pk2(v[0], v[1]); w.y = pk2(v[2], v[3]); return w; }
; __device__ __forceinline__ f32x4 silu4(const f32x4 z) { f32x4 r; r[0] = z[0] * fast_sigmoid(z[0]); r[1] = z[1] * fast_sigmoid(z[1]); r[2] = z[2] * fast_sigmoid(z[2]); r[3] = z[3] * fast_sigmoid(z[3]); return r; }
;     __device__ __forceinline__ void operator()(const AccT& acc, const Unit& u, int wr, int wc, int fr, int fq) const {
;     ...
;                 for (int m = 0; m < 4; ++m) {
;                     const int row = row0 + ai * 128 + m * 16;
;                     f32x4 o[2];
; #pragma unroll
;                     for (int n = 0; n < 2; ++n) { const f32x4 p0 = acc[ai][0][m][n], p1 = acc[ai][1][m][n]; o[n] = ch_tile ? p0 * p1 : silu4(p1) * p0; }
;                     const u32x2 w0 = pk4(o[0]), w1 = pk4(o[1]); const u32x4 pw = {w0.x, w0.y, w1.x, w1.y};
;                     *(u32x4*)(O + (size_t)row * DM) = pw;
;                 }
.LBB0_763:
	v_pk_mul_f32 v[102:103], v[102:103], v[98:99]
	v_pk_mul_f32 v[98:99], v[100:101], v[96:97]
	v_or_b32_e32 v100, 32, v170
	v_ashrrev_i32_e32 v101, 31, v100
	v_lshlrev_b64 v[100:101], 11, v[100:101]
	v_lshl_add_u64 v[100:101], v[136:137], 0, v[100:101]
	s_and_b64 vcc, exec, s[40:41]
	v_pk_mul_f32 v[106:107], v[110:111], v[106:107]
	v_pk_mul_f32 v[104:105], v[108:109], v[104:105]
	v_cvt_pk_bf16_f32 v97, v106, v107
	v_cvt_pk_bf16_f32 v98, v98, v99
	v_cvt_pk_bf16_f32 v99, v102, v103
	s_nop 0
	v_cvt_pk_bf16_f32 v96, v104, v105
	global_store_dwordx4 v[100:101], v[96:99], off nt
	s_cbranch_vccnz .LBB0_765
	s_nop 0
	v_mul_f32_e32 v96, 0xbfb8aa3b, v88
	v_mul_f32_e32 v97, 0xbfb8aa3b, v89
	v_mul_f32_e32 v98, 0xbfb8aa3b, v90
	v_mul_f32_e32 v99, 0xbfb8aa3b, v91
	v_exp_f32_e32 v96, v96
	v_exp_f32_e32 v97, v97
	v_exp_f32_e32 v98, v98
	v_exp_f32_e32 v99, v99
	v_add_f32_e32 v96, 1.0, v96
	v_add_f32_e32 v97, 1.0, v97
	v_add_f32_e32 v98, 1.0, v98
	v_add_f32_e32 v99, 1.0, v99
	v_rcp_f32_e32 v96, v96
	v_rcp_f32_e32 v98, v98
	v_rcp_f32_e32 v99, v99
	v_rcp_f32_e32 v97, v97
	v_pk_mul_f32 v[90:91], v[90:91], v[98:99]
	v_pk_mul_f32 v[88:89], v[88:89], v[96:97]

; __device__ __forceinline__ float fast_sigmoid(float x) { return __builtin_amdgcn_rcpf(1.f + __expf(-x)); }
; __device__ __forceinline__ u32x2 pk4(const f32x4 v) { u32x2 w; w.x = pk2(v[0], v[1]); w.y = pk2(v[2], v[3]); return w; }
; __device__ __forceinline__ f32x4 silu4(const f32x4 z) { f32x4 r; r[0] = z[0] * fast_sigmoid(z[0]); r[1] = z[1] * fast_sigmoid(z[1]); r[2] = z[2] * fast_sigmoid(z[2]); r[3] = z[3] * fast_sigmoid(z[3]); return r; }
;     __device__ __forceinline__ void operator()(const AccT& acc, const Unit& u, int wr, int wc, int fr, int fq) const {
;     ...
;                 for (int m = 0; m < 4; ++m) {
;                     const int row = row0 + ai * 128 + m * 16;
;                     f32x4 o[2];
; #pragma unroll
;                     for (int n = 0; n < 2; ++n) { const f32x4 p0 = acc[ai][0][m][n], p1 = acc[ai][1][m][n]; o[n] = ch_tile ? p0 * p1 : silu4(p1) * p0; }
;                     const u32x2 w0 = pk4(o[0]), w1 = pk4(o[1]); const u32x4 pw = {w0.x, w0.y, w1.x, w1.y};
;                     *(u32x4*)(O + (size_t)row * DM) = pw;
;                 }
.LBB0_767:
	v_pk_mul_f32 v[86:87], v[86:87], v[82:83]
	v_pk_mul_f32 v[82:83], v[84:85], v[80:81]
	v_or_b32_e32 v84, 48, v170
	v_ashrrev_i32_e32 v85, 31, v84
	v_lshlrev_b64 v[84:85], 11, v[84:85]
	v_lshl_add_u64 v[84:85], v[136:137], 0, v[84:85]
	s_and_b64 vcc, exec, s[40:41]
	v_pk_mul_f32 v[90:91], v[94:95], v[90:91]
	v_pk_mul_f32 v[88:89], v[92:93], v[88:89]
	v_cvt_pk_bf16_f32 v81, v90, v91
	v_cvt_pk_bf16_f32 v82, v82, v83
	v_cvt_pk_bf16_f32 v83, v86, v87
	s_nop 0
	v_cvt_pk_bf16_f32 v80, v88, v89
	global_store_dwordx4 v[84:85], v[80:83], off nt
	s_cbranch_vccnz .LBB0_769
	s_nop 0
	v_mul_f32_e32 v80, 0xbfb8aa3b, v72
	v_mul_f32_e32 v81, 0xbfb8aa3b, v73
	v_mul_f32_e32 v82, 0xbfb8aa3b, v74
	v_mul_f32_e32 v83, 0xbfb8aa3b, v75
	v_exp_f32_e32 v80, v80
	v_exp_f32_e32 v81, v81
	v_exp_f32_e32 v82, v82
	v_exp_f32_e32 v83, v83
	v_add_f32_e32 v80, 1.0, v80
	v_add_f32_e32 v81, 1.0, v81
	v_add_f32_e32 v82, 1.0, v82
	v_add_f32_e32 v83, 1.0, v83
	v_rcp_f32_e32 v80, v80
	v_rcp_f32_e32 v82, v82
	v_rcp_f32_e32 v83, v83
	v_rcp_f32_e32 v81, v81
	v_pk_mul_f32 v[74:75], v[74:75], v[82:83]
	v_pk_mul_f32 v[72:73], v[72:73], v[80:81]

; __device__ __forceinline__ float fast_sigmoid(float x) { return __builtin_amdgcn_rcpf(1.f + __expf(-x)); }
; __device__ __forceinline__ u32x2 pk4(const f32x4 v) { u32x2 w; w.x = pk2(v[0], v[1]); w.y = pk2(v[2], v[3]); return w; }
; __device__ __forceinline__ f32x4 silu4(const f32x4 z) { f32x4 r; r[0] = z[0] * fast_sigmoid(z[0]); r[1] = z[1] * fast_sigmoid(z[1]); r[2] = z[2] * fast_sigmoid(z[2]); r[3] = z[3] * fast_sigmoid(z[3]); return r; }
;     __device__ __forceinline__ void operator()(const AccT& acc, const Unit& u, int wr, int wc, int fr, int fq) const {
;     ...
;                 for (int m = 0; m < 4; ++m) {
;                     const int row = row0 + ai * 128 + m * 16;
;                     f32x4 o[2];
; #pragma unroll
;                     for (int n = 0; n < 2; ++n) { const f32x4 p0 = acc[ai][0][m][n], p1 = acc[ai][1][m][n]; o[n] = ch_tile ? p0 * p1 : silu4(p1) * p0; }
;                     const u32x2 w0 = pk4(o[0]), w1 = pk4(o[1]); const u32x4 pw = {w0.x, w0.y, w1.x, w1.y};
;                     *(u32x4*)(O + (size_t)row * DM) = pw;
;                 }
.LBB0_771:
	v_pk_mul_f32 v[70:71], v[70:71], v[66:67]
	v_pk_mul_f32 v[66:67], v[68:69], v[64:65]
	v_lshlrev_b64 v[68:69], 11, v[170:171]
	v_lshl_add_u64 v[68:69], v[136:137], 0, v[68:69]
	v_add_co_u32_e32 v68, vcc, 0x40000, v68
	v_pk_mul_f32 v[74:75], v[78:79], v[74:75]
	s_nop 0
	v_addc_co_u32_e32 v69, vcc, 0, v69, vcc
	s_and_b64 vcc, exec, s[40:41]
	v_pk_mul_f32 v[72:73], v[76:77], v[72:73]
	v_cvt_pk_bf16_f32 v65, v74, v75
	v_cvt_pk_bf16_f32 v66, v66, v67
	v_cvt_pk_bf16_f32 v67, v70, v71
	s_nop 0
	v_cvt_pk_bf16_f32 v64, v72, v73
	global_store_dwordx4 v[68:69], v[64:67], off nt
	s_cbranch_vccnz .LBB0_773
	s_nop 0
	v_mul_f32_e32 v64, 0xbfb8aa3b, v56
	v_mul_f32_e32 v65, 0xbfb8aa3b, v57
	v_mul_f32_e32 v66, 0xbfb8aa3b, v58
	v_mul_f32_e32 v67, 0xbfb8aa3b, v59
	v_exp_f32_e32 v64, v64
	v_exp_f32_e32 v65, v65
	v_exp_f32_e32 v66, v66
	v_exp_f32_e32 v67, v67
	v_add_f32_e32 v64, 1.0, v64
	v_add_f32_e32 v65, 1.0, v65
	v_add_f32_e32 v66, 1.0, v66
	v_add_f32_e32 v67, 1.0, v67
	v_rcp_f32_e32 v64, v64
	v_rcp_f32_e32 v66, v66
	v_rcp_f32_e32 v67, v67
	v_rcp_f32_e32 v65, v65
	v_pk_mul_f32 v[58:59], v[58:59], v[66:67]
	v_pk_mul_f32 v[56:57], v[56:57], v[64:65]

; __device__ __forceinline__ float fast_sigmoid(float x) { return __builtin_amdgcn_rcpf(1.f + __expf(-x)); }
; __device__ __forceinline__ u32x2 pk4(const f32x4 v) { u32x2 w; w.x = pk2(v[0], v[1]); w.y = pk2(v[2], v[3]); return w; }
; __device__ __forceinline__ f32x4 silu4(const f32x4 z) { f32x4 r; r[0] = z[0] * fast_sigmoid(z[0]); r[1] = z[1] * fast_sigmoid(z[1]); r[2] = z[2] * fast_sigmoid(z[2]); r[3] = z[3] * fast_sigmoid(z[3]); return r; }
;     __device__ __forceinline__ void operator()(const AccT& acc, const Unit& u, int wr, int wc, int fr, int fq) const {
;     ...
;                 for (int m = 0; m < 4; ++m) {
;                     const int row = row0 + ai * 128 + m * 16;
;                     f32x4 o[2];
; #pragma unroll
;                     for (int n = 0; n < 2; ++n) { const f32x4 p0 = acc[ai][0][m][n], p1 = acc[ai][1][m][n]; o[n] = ch_tile ? p0 * p1 : silu4(p1) * p0; }
;                     const u32x2 w0 = pk4(o[0]), w1 = pk4(o[1]); const u32x4 pw = {w0.x, w0.y, w1.x, w1.y};
;                     *(u32x4*)(O + (size_t)row * DM) = pw;
;                 }
.LBB0_775:
	v_pk_mul_f32 v[54:55], v[54:55], v[50:51]
	v_pk_mul_f32 v[50:51], v[52:53], v[48:49]
	v_lshlrev_b64 v[52:53], 11, v[170:171]
	v_lshl_add_u64 v[52:53], v[136:137], 0, v[52:53]
	v_add_co_u32_e32 v52, vcc, 0x48000, v52
	v_pk_mul_f32 v[58:59], v[62:63], v[58:59]
	s_nop 0
	v_addc_co_u32_e32 v53, vcc, 0, v53, vcc
	s_and_b64 vcc, exec, s[40:41]
	v_pk_mul_f32 v[56:57], v[60:61], v[56:57]
	v_cvt_pk_bf16_f32 v49, v58, v59
	v_cvt_pk_bf16_f32 v50, v50, v51
	v_cvt_pk_bf16_f32 v51, v54, v55
	s_nop 0
	v_cvt_pk_bf16_f32 v48, v56, v57
	global_store_dwordx4 v[52:53], v[48:51], off nt
	s_cbranch_vccnz .LBB0_777
	s_nop 0
	v_mul_f32_e32 v48, 0xbfb8aa3b, v40
	v_mul_f32_e32 v49, 0xbfb8aa3b, v41
	v_mul_f32_e32 v50, 0xbfb8aa3b, v42
	v_mul_f32_e32 v51, 0xbfb8aa3b, v43
	v_exp_f32_e32 v48, v48
	v_exp_f32_e32 v49, v49
	v_exp_f32_e32 v50, v50
	v_exp_f32_e32 v51, v51
	v_add_f32_e32 v48, 1.0, v48
	v_add_f32_e32 v49, 1.0, v49
	v_add_f32_e32 v50, 1.0, v50
	v_add_f32_e32 v51, 1.0, v51
	v_rcp_f32_e32 v48, v48
	v_rcp_f32_e32 v50, v50
	v_rcp_f32_e32 v51, v51
	v_rcp_f32_e32 v49, v49
	v_pk_mul_f32 v[42:43], v[42:43], v[50:51]
	v_pk_mul_f32 v[40:41], v[40:41], v[48:49]

; __device__ __forceinline__ float fast_sigmoid(float x) { return __builtin_amdgcn_rcpf(1.f + __expf(-x)); }
; __device__ __forceinline__ u32x2 pk4(const f32x4 v) { u32x2 w; w.x = pk2(v[0], v[1]); w.y = pk2(v[2], v[3]); return w; }
; __device__ __forceinline__ f32x4 silu4(const f32x4 z) { f32x4 r; r[0] = z[0] * fast_sigmoid(z[0]); r[1] = z[1] * fast_sigmoid(z[1]); r[2] = z[2] * fast_sigmoid(z[2]); r[3] = z[3] * fast_sigmoid(z[3]); return r; }
;     __device__ __forceinline__ void operator()(const AccT& acc, const Unit& u, int wr, int wc, int fr, int fq) const {
;     ...
;                 for (int m = 0; m < 4; ++m) {
;                     const int row = row0 + ai * 128 + m * 16;
;                     f32x4 o[2];
; #pragma unroll
;                     for (int n = 0; n < 2; ++n) { const f32x4 p0 = acc[ai][0][m][n], p1 = acc[ai][1][m][n]; o[n] = ch_tile ? p0 * p1 : silu4(p1) * p0; }
;                     const u32x2 w0 = pk4(o[0]), w1 = pk4(o[1]); const u32x4 pw = {w0.x, w0.y, w1.x, w1.y};
;                     *(u32x4*)(O + (size_t)row * DM) = pw;
;                 }
.LBB0_779:
	v_pk_mul_f32 v[38:39], v[38:39], v[34:35]
	v_pk_mul_f32 v[34:35], v[36:37], v[32:33]
	v_lshlrev_b64 v[36:37], 11, v[170:171]
	v_lshl_add_u64 v[36:37], v[136:137], 0, v[36:37]
	v_add_co_u32_e32 v36, vcc, 0x50000, v36
	v_pk_mul_f32 v[42:43], v[46:47], v[42:43]
	s_nop 0
	v_addc_co_u32_e32 v37, vcc, 0, v37, vcc
	s_and_b64 vcc, exec, s[40:41]
	v_pk_mul_f32 v[40:41], v[44:45], v[40:41]
	v_cvt_pk_bf16_f32 v33, v42, v43
	v_cvt_pk_bf16_f32 v34, v34, v35
	v_cvt_pk_bf16_f32 v35, v38, v39
	s_nop 0
	v_cvt_pk_bf16_f32 v32, v40, v41
	global_store_dwordx4 v[36:37], v[32:35], off nt
	s_cbranch_vccnz .LBB0_781
	s_nop 0
	v_mul_f32_e32 v32, 0xbfb8aa3b, v24
	v_mul_f32_e32 v33, 0xbfb8aa3b, v25
	v_mul_f32_e32 v34, 0xbfb8aa3b, v26
	v_mul_f32_e32 v35, 0xbfb8aa3b, v27
	v_exp_f32_e32 v32, v32
	v_exp_f32_e32 v33, v33
	v_exp_f32_e32 v34, v34
	v_exp_f32_e32 v35, v35
	v_add_f32_e32 v32, 1.0, v32
	v_add_f32_e32 v33, 1.0, v33
	v_add_f32_e32 v34, 1.0, v34
	v_add_f32_e32 v35, 1.0, v35
	v_rcp_f32_e32 v32, v32
	v_rcp_f32_e32 v34, v34
	v_rcp_f32_e32 v35, v35
	v_rcp_f32_e32 v33, v33
	v_pk_mul_f32 v[26:27], v[26:27], v[34:35]
	v_pk_mul_f32 v[24:25], v[24:25], v[32:33]

; __device__ __forceinline__ f32x4 silu4(const f32x4 z) { f32x4 r; r[0] = z[0] * fast_sigmoid(z[0]); r[1] = z[1] * fast_sigmoid(z[1]); r[2] = z[2] * fast_sigmoid(z[2]); r[3] = z[3] * fast_sigmoid(z[3]); return r; }
; __device__ __forceinline__ u32x2 pk4(const f32x4 v) { u32x2 w; w.x = pk2(v[0], v[1]); w.y = pk2(v[2], v[3]); return w; }
;     __device__ __forceinline__ void operator()(const AccT& acc, const Unit& u, int wr, int wc, int fr, int fq) const {
;     ...
;                 for (int m = 0; m < 4; ++m) {
;                     const int row = row0 + ai * 128 + m * 16;
;                     f32x4 o[2];
; #pragma unroll
;                     for (int n = 0; n < 2; ++n) { const f32x4 p0 = acc[ai][0][m][n], p1 = acc[ai][1][m][n]; o[n] = ch_tile ? p0 * p1 : silu4(p1) * p0; }
;                     const u32x2 w0 = pk4(o[0]), w1 = pk4(o[1]); const u32x4 pw = {w0.x, w0.y, w1.x, w1.y};
;                     *(u32x4*)(O + (size_t)row * DM) = pw;
;                 }
.LBB0_783:
	v_pk_mul_f32 v[22:23], v[22:23], v[18:19]
	v_pk_mul_f32 v[18:19], v[20:21], v[16:17]
	v_lshlrev_b64 v[20:21], 11, v[170:171]
	v_lshl_add_u64 v[20:21], v[136:137], 0, v[20:21]
	v_add_co_u32_e32 v20, vcc, 0x58000, v20
	v_pk_mul_f32 v[26:27], v[30:31], v[26:27]
	s_nop 0
	v_addc_co_u32_e32 v21, vcc, 0, v21, vcc
	v_pk_mul_f32 v[24:25], v[28:29], v[24:25]
	v_cvt_pk_bf16_f32 v17, v26, v27
	v_cvt_pk_bf16_f32 v18, v18, v19
	v_cvt_pk_bf16_f32 v19, v22, v23
	s_nop 0
	v_cvt_pk_bf16_f32 v16, v24, v25
	global_store_dwordx4 v[20:21], v[16:19], off nt
	s_and_b64 vcc, exec, s[38:39]
	s_mov_b64 s[0:1], -1
	s_cbranch_vccnz .LBB0_705
	s_branch .LBB0_1078

; __device__ __forceinline__ f32x4 silu4(const f32x4 z) { f32x4 r; r[0] = z[0] * fast_sigmoid(z[0]); r[1] = z[1] * fast_sigmoid(z[1]); r[2] = z[2] * fast_sigmoid(z[2]); r[3] = z[3] * fast_sigmoid(z[3]); return r; }
; __device__ __forceinline__ f32x4 sigm4(const f32x4 z) { f32x4 r; r[0] = fast_sigmoid(z[0]); r[1] = fast_sigmoid(z[1]); r[2] = fast_sigmoid(z[2]); r[3] = fast_sigmoid(z[3]); return r; }
; __device__ __forceinline__ u32x2 pk4(const f32x4 v) { u32x2 w; w.x = pk2(v[0], v[1]); w.y = pk2(v[2], v[3]); return w; }
;     __device__ __forceinline__ void operator()(const AccT& acc, const Unit& u, int wr, int wc, int fr, int fq) const {
;     ...
;                     const int row = row0 + ai * 128 + m * 16;
;                     float* vo = (row < MP ? vp + (size_t)row * DM : vs + (size_t)(row - MP) * DM) + colt;
;                     const bool vok = (grp == 0) && (row < MV);
; #pragma unroll
;                     for (int bj = 0; bj < 2; ++bj) {
;                         f32x4 v0 = acc[ai][bj][m][0], v1 = acc[ai][bj][m][1];
;                         if (vok) { __builtin_nontemporal_store(v0, (f32x4*)(vo + bj * 128)); __builtin_nontemporal_store(v1, (f32x4*)(vo + bj * 128 + 4)); }
;                         if (grp == 1) { v0 = silu4(v0); v1 = silu4(v1); } else if (grp >= 2) { v0 = sigm4(v0); v1 = sigm4(v1); }
;                         const u32x2 p0 = pk4(v0), p1 = pk4(v1); const u32x4 pw = {p0.x, p0.y, p1.x, p1.y};
;                         *(u32x4*)(O + (size_t)row * DM + bj * 128) = pw;
.LBB0_786:
	v_lshlrev_b64 v[146:147], 11, v[146:147]
	v_lshl_add_u64 v[146:147], v[144:145], 0, v[146:147]
	v_cvt_pk_bf16_f32 v150, v150, v151
	v_cvt_pk_bf16_f32 v151, v152, v153
	v_cvt_pk_bf16_f32 v152, v154, v155
	v_cvt_pk_bf16_f32 v153, v172, v173
	global_store_dwordx4 v[146:147], v[150:153], off nt
	s_and_saveexec_b64 s[22:23], s[20:21]
	s_cbranch_execz .LBB0_788
	global_store_dwordx4 v[148:149], v[120:123], off offset:512 nt
	global_store_dwordx4 v[148:149], v[112:115], off offset:528 nt

; __device__ __forceinline__ f32x4 silu4(const f32x4 z) { f32x4 r; r[0] = z[0] * fast_sigmoid(z[0]); r[1] = z[1] * fast_sigmoid(z[1]); r[2] = z[2] * fast_sigmoid(z[2]); r[3] = z[3] * fast_sigmoid(z[3]); return r; }
; __device__ __forceinline__ f32x4 sigm4(const f32x4 z) { f32x4 r; r[0] = fast_sigmoid(z[0]); r[1] = fast_sigmoid(z[1]); r[2] = fast_sigmoid(z[2]); r[3] = fast_sigmoid(z[3]); return r; }
; __device__ __forceinline__ u32x2 pk4(const f32x4 v) { u32x2 w; w.x = pk2(v[0], v[1]); w.y = pk2(v[2], v[3]); return w; }
;     __device__ __forceinline__ void operator()(const AccT& acc, const Unit& u, int wr, int wc, int fr, int fq) const {
;     ...
;                     float* vo = (row < MP ? vp + (size_t)row * DM : vs + (size_t)(row - MP) * DM) + colt;
;     ...
;                     for (int bj = 0; bj < 2; ++bj) {
;                         f32x4 v0 = acc[ai][bj][m][0], v1 = acc[ai][bj][m][1];
;                         if (vok) { __builtin_nontemporal_store(v0, (f32x4*)(vo + bj * 128)); __builtin_nontemporal_store(v1, (f32x4*)(vo + bj * 128 + 4)); }
;                         if (grp == 1) { v0 = silu4(v0); v1 = silu4(v1); } else if (grp >= 2) { v0 = sigm4(v0); v1 = sigm4(v1); }
;                         const u32x2 p0 = pk4(v0), p1 = pk4(v1); const u32x4 pw = {p0.x, p0.y, p1.x, p1.y};
;                         *(u32x4*)(O + (size_t)row * DM + bj * 128) = pw;
.LBB0_794:
	v_cvt_pk_bf16_f32 v148, v148, v149
	v_cvt_pk_bf16_f32 v149, v150, v151
	s_nop 0
	v_cvt_pk_bf16_f32 v150, v152, v153
	v_cvt_pk_bf16_f32 v151, v154, v155
	global_store_dwordx4 v[146:147], v[148:151], off offset:256 nt
	v_or_b32_e32 v146, 32, v170
	v_cmp_lt_i32_e32 vcc, s93, v146
	s_and_saveexec_b64 s[20:21], vcc
	s_xor_b64 s[20:21], exec, s[20:21]
	s_cbranch_execz .LBB0_796
	v_add_u32_e32 v148, 0xffff7fe0, v170
	v_mov_b32_e32 v149, v181
	v_readlane_b32 s22, v252, 38
	v_lshlrev_b64 v[148:149], 12, v[148:149]
	v_readlane_b32 s23, v252, 39
	v_mov_b32_e32 v147, v181
	s_nop 0
	v_lshl_add_u64 v[148:149], s[22:23], 0, v[148:149]

; __device__ __forceinline__ f32x4 silu4(const f32x4 z) { f32x4 r; r[0] = z[0] * fast_sigmoid(z[0]); r[1] = z[1] * fast_sigmoid(z[1]); r[2] = z[2] * fast_sigmoid(z[2]); r[3] = z[3] * fast_sigmoid(z[3]); return r; }
; __device__ __forceinline__ f32x4 sigm4(const f32x4 z) { f32x4 r; r[0] = fast_sigmoid(z[0]); r[1] = fast_sigmoid(z[1]); r[2] = fast_sigmoid(z[2]); r[3] = fast_sigmoid(z[3]); return r; }
; __device__ __forceinline__ u32x2 pk4(const f32x4 v) { u32x2 w; w.x = pk2(v[0], v[1]); w.y = pk2(v[2], v[3]); return w; }
;     __device__ __forceinline__ void operator()(const AccT& acc, const Unit& u, int wr, int wc, int fr, int fq) const {
;     ...
;                     const int row = row0 + ai * 128 + m * 16;
;                     float* vo = (row < MP ? vp + (size_t)row * DM : vs + (size_t)(row - MP) * DM) + colt;
;                     const bool vok = (grp == 0) && (row < MV);
; #pragma unroll
;                     for (int bj = 0; bj < 2; ++bj) {
;                         f32x4 v0 = acc[ai][bj][m][0], v1 = acc[ai][bj][m][1];
;                         if (vok) { __builtin_nontemporal_store(v0, (f32x4*)(vo + bj * 128)); __builtin_nontemporal_store(v1, (f32x4*)(vo + bj * 128 + 4)); }
;                         if (grp == 1) { v0 = silu4(v0); v1 = silu4(v1); } else if (grp >= 2) { v0 = sigm4(v0); v1 = sigm4(v1); }
;                         const u32x2 p0 = pk4(v0), p1 = pk4(v1); const u32x4 pw = {p0.x, p0.y, p1.x, p1.y};
;                         *(u32x4*)(O + (size_t)row * DM + bj * 128) = pw;
.LBB0_806:
	v_lshlrev_b64 v[146:147], 11, v[146:147]
	v_lshl_add_u64 v[146:147], v[144:145], 0, v[146:147]
	v_cvt_pk_bf16_f32 v150, v150, v151
	v_cvt_pk_bf16_f32 v151, v152, v153
	v_cvt_pk_bf16_f32 v152, v154, v155
	v_cvt_pk_bf16_f32 v153, v172, v173
	global_store_dwordx4 v[146:147], v[150:153], off nt
	s_and_saveexec_b64 s[22:23], s[20:21]
	s_cbranch_execz .LBB0_808
	global_store_dwordx4 v[148:149], v[104:107], off offset:512 nt
	global_store_dwordx4 v[148:149], v[96:99], off offset:528 nt

; __device__ __forceinline__ f32x4 silu4(const f32x4 z) { f32x4 r; r[0] = z[0] * fast_sigmoid(z[0]); r[1] = z[1] * fast_sigmoid(z[1]); r[2] = z[2] * fast_sigmoid(z[2]); r[3] = z[3] * fast_sigmoid(z[3]); return r; }
; __device__ __forceinline__ f32x4 sigm4(const f32x4 z) { f32x4 r; r[0] = fast_sigmoid(z[0]); r[1] = fast_sigmoid(z[1]); r[2] = fast_sigmoid(z[2]); r[3] = fast_sigmoid(z[3]); return r; }
; __device__ __forceinline__ u32x2 pk4(const f32x4 v) { u32x2 w; w.x = pk2(v[0], v[1]); w.y = pk2(v[2], v[3]); return w; }
;     __device__ __forceinline__ void operator()(const AccT& acc, const Unit& u, int wr, int wc, int fr, int fq) const {
;     ...
;                     float* vo = (row < MP ? vp + (size_t)row * DM : vs + (size_t)(row - MP) * DM) + colt;
;     ...
;                     for (int bj = 0; bj < 2; ++bj) {
;                         f32x4 v0 = acc[ai][bj][m][0], v1 = acc[ai][bj][m][1];
;                         if (vok) { __builtin_nontemporal_store(v0, (f32x4*)(vo + bj * 128)); __builtin_nontemporal_store(v1, (f32x4*)(vo + bj * 128 + 4)); }
;                         if (grp == 1) { v0 = silu4(v0); v1 = silu4(v1); } else if (grp >= 2) { v0 = sigm4(v0); v1 = sigm4(v1); }
;                         const u32x2 p0 = pk4(v0), p1 = pk4(v1); const u32x4 pw = {p0.x, p0.y, p1.x, p1.y};
;                         *(u32x4*)(O + (size_t)row * DM + bj * 128) = pw;
.LBB0_814:
	v_cvt_pk_bf16_f32 v148, v148, v149
	v_cvt_pk_bf16_f32 v149, v150, v151
	s_nop 0
	v_cvt_pk_bf16_f32 v150, v152, v153
	v_cvt_pk_bf16_f32 v151, v154, v155
	global_store_dwordx4 v[146:147], v[148:151], off offset:256 nt
	v_or_b32_e32 v146, 48, v170
	v_cmp_lt_i32_e32 vcc, s93, v146
	s_and_saveexec_b64 s[20:21], vcc
	s_xor_b64 s[20:21], exec, s[20:21]
	s_cbranch_execz .LBB0_816
	v_add_u32_e32 v148, 0xffff7ff0, v170
	v_mov_b32_e32 v149, v181
	v_readlane_b32 s22, v252, 38
	v_lshlrev_b64 v[148:149], 12, v[148:149]
	v_readlane_b32 s23, v252, 39
	v_mov_b32_e32 v147, v181
	s_nop 0
	v_lshl_add_u64 v[148:149], s[22:23], 0, v[148:149]

; __device__ __forceinline__ f32x4 silu4(const f32x4 z) { f32x4 r; r[0] = z[0] * fast_sigmoid(z[0]); r[1] = z[1] * fast_sigmoid(z[1]); r[2] = z[2] * fast_sigmoid(z[2]); r[3] = z[3] * fast_sigmoid(z[3]); return r; }
; __device__ __forceinline__ f32x4 sigm4(const f32x4 z) { f32x4 r; r[0] = fast_sigmoid(z[0]); r[1] = fast_sigmoid(z[1]); r[2] = fast_sigmoid(z[2]); r[3] = fast_sigmoid(z[3]); return r; }
; __device__ __forceinline__ u32x2 pk4(const f32x4 v) { u32x2 w; w.x = pk2(v[0], v[1]); w.y = pk2(v[2], v[3]); return w; }
;     __device__ __forceinline__ void operator()(const AccT& acc, const Unit& u, int wr, int wc, int fr, int fq) const {
;     ...
;                     const int row = row0 + ai * 128 + m * 16;
;                     float* vo = (row < MP ? vp + (size_t)row * DM : vs + (size_t)(row - MP) * DM) + colt;
;                     const bool vok = (grp == 0) && (row < MV);
; #pragma unroll
;                     for (int bj = 0; bj < 2; ++bj) {
;                         f32x4 v0 = acc[ai][bj][m][0], v1 = acc[ai][bj][m][1];
;                         if (vok) { __builtin_nontemporal_store(v0, (f32x4*)(vo + bj * 128)); __builtin_nontemporal_store(v1, (f32x4*)(vo + bj * 128 + 4)); }
;                         if (grp == 1) { v0 = silu4(v0); v1 = silu4(v1); } else if (grp >= 2) { v0 = sigm4(v0); v1 = sigm4(v1); }
;                         const u32x2 p0 = pk4(v0), p1 = pk4(v1); const u32x4 pw = {p0.x, p0.y, p1.x, p1.y};
;                         *(u32x4*)(O + (size_t)row * DM + bj * 128) = pw;
.LBB0_826:
	v_lshlrev_b64 v[146:147], 11, v[146:147]
	v_lshl_add_u64 v[146:147], v[144:145], 0, v[146:147]
	v_cvt_pk_bf16_f32 v150, v150, v151
	v_cvt_pk_bf16_f32 v151, v152, v153
	v_cvt_pk_bf16_f32 v152, v154, v155
	v_cvt_pk_bf16_f32 v153, v172, v173
	global_store_dwordx4 v[146:147], v[150:153], off nt
	s_and_saveexec_b64 s[22:23], s[20:21]
	s_cbranch_execz .LBB0_828
	global_store_dwordx4 v[148:149], v[88:91], off offset:512 nt
	global_store_dwordx4 v[148:149], v[80:83], off offset:528 nt

; __device__ __forceinline__ f32x4 silu4(const f32x4 z) { f32x4 r; r[0] = z[0] * fast_sigmoid(z[0]); r[1] = z[1] * fast_sigmoid(z[1]); r[2] = z[2] * fast_sigmoid(z[2]); r[3] = z[3] * fast_sigmoid(z[3]); return r; }
; __device__ __forceinline__ f32x4 sigm4(const f32x4 z) { f32x4 r; r[0] = fast_sigmoid(z[0]); r[1] = fast_sigmoid(z[1]); r[2] = fast_sigmoid(z[2]); r[3] = fast_sigmoid(z[3]); return r; }
; __device__ __forceinline__ u32x2 pk4(const f32x4 v) { u32x2 w; w.x = pk2(v[0], v[1]); w.y = pk2(v[2], v[3]); return w; }
;     __device__ __forceinline__ void operator()(const AccT& acc, const Unit& u, int wr, int wc, int fr, int fq) const {
;     ...
;                     float* vo = (row < MP ? vp + (size_t)row * DM : vs + (size_t)(row - MP) * DM) + colt;
;     ...
;                     for (int bj = 0; bj < 2; ++bj) {
;                         f32x4 v0 = acc[ai][bj][m][0], v1 = acc[ai][bj][m][1];
;                         if (vok) { __builtin_nontemporal_store(v0, (f32x4*)(vo + bj * 128)); __builtin_nontemporal_store(v1, (f32x4*)(vo + bj * 128 + 4)); }
;                         if (grp == 1) { v0 = silu4(v0); v1 = silu4(v1); } else if (grp >= 2) { v0 = sigm4(v0); v1 = sigm4(v1); }
;                         const u32x2 p0 = pk4(v0), p1 = pk4(v1); const u32x4 pw = {p0.x, p0.y, p1.x, p1.y};
;                         *(u32x4*)(O + (size_t)row * DM + bj * 128) = pw;
.LBB0_834:
	s_movk_i32 s8, 0x7fbf
	v_cvt_pk_bf16_f32 v148, v148, v149
	v_cvt_pk_bf16_f32 v149, v150, v151
	v_cvt_pk_bf16_f32 v150, v152, v153
	v_cvt_pk_bf16_f32 v151, v154, v155
	global_store_dwordx4 v[146:147], v[148:151], off offset:256 nt
	v_add_u32_e32 v146, 0x80, v170
	v_cmp_lt_i32_e32 vcc, s8, v170
	s_and_saveexec_b64 s[20:21], vcc
	s_xor_b64 s[20:21], exec, s[20:21]
	s_cbranch_execz .LBB0_836
	v_add_u32_e32 v148, 0xffff8040, v170
	v_mov_b32_e32 v149, v181
	v_readlane_b32 s22, v252, 38
	v_lshlrev_b64 v[148:149], 12, v[148:149]
	v_readlane_b32 s23, v252, 39
	v_mov_b32_e32 v147, v181
	s_nop 0
	v_lshl_add_u64 v[148:149], s[22:23], 0, v[148:149]

; __device__ __forceinline__ f32x4 silu4(const f32x4 z) { f32x4 r; r[0] = z[0] * fast_sigmoid(z[0]); r[1] = z[1] * fast_sigmoid(z[1]); r[2] = z[2] * fast_sigmoid(z[2]); r[3] = z[3] * fast_sigmoid(z[3]); return r; }
; __device__ __forceinline__ f32x4 sigm4(const f32x4 z) { f32x4 r; r[0] = fast_sigmoid(z[0]); r[1] = fast_sigmoid(z[1]); r[2] = fast_sigmoid(z[2]); r[3] = fast_sigmoid(z[3]); return r; }
; __device__ __forceinline__ u32x2 pk4(const f32x4 v) { u32x2 w; w.x = pk2(v[0], v[1]); w.y = pk2(v[2], v[3]); return w; }
;     __device__ __forceinline__ void operator()(const AccT& acc, const Unit& u, int wr, int wc, int fr, int fq) const {
;     ...
;                     const int row = row0 + ai * 128 + m * 16;
;                     float* vo = (row < MP ? vp + (size_t)row * DM : vs + (size_t)(row - MP) * DM) + colt;
;                     const bool vok = (grp == 0) && (row < MV);
; #pragma unroll
;                     for (int bj = 0; bj < 2; ++bj) {
;                         f32x4 v0 = acc[ai][bj][m][0], v1 = acc[ai][bj][m][1];
;                         if (vok) { __builtin_nontemporal_store(v0, (f32x4*)(vo + bj * 128)); __builtin_nontemporal_store(v1, (f32x4*)(vo + bj * 128 + 4)); }
;                         if (grp == 1) { v0 = silu4(v0); v1 = silu4(v1); } else if (grp >= 2) { v0 = sigm4(v0); v1 = sigm4(v1); }
;                         const u32x2 p0 = pk4(v0), p1 = pk4(v1); const u32x4 pw = {p0.x, p0.y, p1.x, p1.y};
;                         *(u32x4*)(O + (size_t)row * DM + bj * 128) = pw;
.LBB0_846:
	v_lshlrev_b64 v[146:147], 11, v[146:147]
	v_lshl_add_u64 v[146:147], v[144:145], 0, v[146:147]
	v_cvt_pk_bf16_f32 v150, v150, v151
	v_cvt_pk_bf16_f32 v151, v152, v153
	v_cvt_pk_bf16_f32 v152, v154, v155
	v_cvt_pk_bf16_f32 v153, v172, v173
	global_store_dwordx4 v[146:147], v[150:153], off nt
	s_and_saveexec_b64 s[22:23], s[20:21]
	s_cbranch_execz .LBB0_848
	global_store_dwordx4 v[148:149], v[72:75], off offset:512 nt
	global_store_dwordx4 v[148:149], v[64:67], off offset:528 nt

; __device__ __forceinline__ f32x4 silu4(const f32x4 z) { f32x4 r; r[0] = z[0] * fast_sigmoid(z[0]); r[1] = z[1] * fast_sigmoid(z[1]); r[2] = z[2] * fast_sigmoid(z[2]); r[3] = z[3] * fast_sigmoid(z[3]); return r; }
; __device__ __forceinline__ f32x4 sigm4(const f32x4 z) { f32x4 r; r[0] = fast_sigmoid(z[0]); r[1] = fast_sigmoid(z[1]); r[2] = fast_sigmoid(z[2]); r[3] = fast_sigmoid(z[3]); return r; }
; __device__ __forceinline__ u32x2 pk4(const f32x4 v) { u32x2 w; w.x = pk2(v[0], v[1]); w.y = pk2(v[2], v[3]); return w; }
;     __device__ __forceinline__ void operator()(const AccT& acc, const Unit& u, int wr, int wc, int fr, int fq) const {
;     ...
;                     float* vo = (row < MP ? vp + (size_t)row * DM : vs + (size_t)(row - MP) * DM) + colt;
;     ...
;                     for (int bj = 0; bj < 2; ++bj) {
;                         f32x4 v0 = acc[ai][bj][m][0], v1 = acc[ai][bj][m][1];
;                         if (vok) { __builtin_nontemporal_store(v0, (f32x4*)(vo + bj * 128)); __builtin_nontemporal_store(v1, (f32x4*)(vo + bj * 128 + 4)); }
;                         if (grp == 1) { v0 = silu4(v0); v1 = silu4(v1); } else if (grp >= 2) { v0 = sigm4(v0); v1 = sigm4(v1); }
;                         const u32x2 p0 = pk4(v0), p1 = pk4(v1); const u32x4 pw = {p0.x, p0.y, p1.x, p1.y};
;                         *(u32x4*)(O + (size_t)row * DM + bj * 128) = pw;
.LBB0_854:
	s_movk_i32 s8, 0x7faf
	v_cvt_pk_bf16_f32 v148, v148, v149
	v_cvt_pk_bf16_f32 v149, v150, v151
	v_cvt_pk_bf16_f32 v150, v152, v153
	v_cvt_pk_bf16_f32 v151, v154, v155
	global_store_dwordx4 v[146:147], v[148:151], off offset:256 nt
	v_add_u32_e32 v146, 0x90, v170
	v_cmp_lt_i32_e32 vcc, s8, v170
	s_and_saveexec_b64 s[20:21], vcc
	s_xor_b64 s[20:21], exec, s[20:21]
	s_cbranch_execz .LBB0_856
	v_add_u32_e32 v148, 0xffff8050, v170
	v_mov_b32_e32 v149, v181
	v_readlane_b32 s22, v252, 38
	v_lshlrev_b64 v[148:149], 12, v[148:149]
	v_readlane_b32 s23, v252, 39
	v_mov_b32_e32 v147, v181
	s_nop 0
	v_lshl_add_u64 v[148:149], s[22:23], 0, v[148:149]

; __device__ __forceinline__ f32x4 silu4(const f32x4 z) { f32x4 r; r[0] = z[0] * fast_sigmoid(z[0]); r[1] = z[1] * fast_sigmoid(z[1]); r[2] = z[2] * fast_sigmoid(z[2]); r[3] = z[3] * fast_sigmoid(z[3]); return r; }
; __device__ __forceinline__ f32x4 sigm4(const f32x4 z) { f32x4 r; r[0] = fast_sigmoid(z[0]); r[1] = fast_sigmoid(z[1]); r[2] = fast_sigmoid(z[2]); r[3] = fast_sigmoid(z[3]); return r; }
; __device__ __forceinline__ u32x2 pk4(const f32x4 v) { u32x2 w; w.x = pk2(v[0], v[1]); w.y = pk2(v[2], v[3]); return w; }
;     __device__ __forceinline__ void operator()(const AccT& acc, const Unit& u, int wr, int wc, int fr, int fq) const {
;     ...
;                     const int row = row0 + ai * 128 + m * 16;
;                     float* vo = (row < MP ? vp + (size_t)row * DM : vs + (size_t)(row - MP) * DM) + colt;
;                     const bool vok = (grp == 0) && (row < MV);
; #pragma unroll
;                     for (int bj = 0; bj < 2; ++bj) {
;                         f32x4 v0 = acc[ai][bj][m][0], v1 = acc[ai][bj][m][1];
;                         if (vok) { __builtin_nontemporal_store(v0, (f32x4*)(vo + bj * 128)); __builtin_nontemporal_store(v1, (f32x4*)(vo + bj * 128 + 4)); }
;                         if (grp == 1) { v0 = silu4(v0); v1 = silu4(v1); } else if (grp >= 2) { v0 = sigm4(v0); v1 = sigm4(v1); }
;                         const u32x2 p0 = pk4(v0), p1 = pk4(v1); const u32x4 pw = {p0.x, p0.y, p1.x, p1.y};
;                         *(u32x4*)(O + (size_t)row * DM + bj * 128) = pw;
.LBB0_866:
	v_lshlrev_b64 v[146:147], 11, v[146:147]
	v_lshl_add_u64 v[146:147], v[144:145], 0, v[146:147]
	v_cvt_pk_bf16_f32 v150, v150, v151
	v_cvt_pk_bf16_f32 v151, v152, v153
	v_cvt_pk_bf16_f32 v152, v154, v155
	v_cvt_pk_bf16_f32 v153, v172, v173
	global_store_dwordx4 v[146:147], v[150:153], off nt
	s_and_saveexec_b64 s[22:23], s[20:21]
	s_cbranch_execz .LBB0_868
	global_store_dwordx4 v[148:149], v[56:59], off offset:512 nt
	global_store_dwordx4 v[148:149], v[48:51], off offset:528 nt

; __device__ __forceinline__ f32x4 silu4(const f32x4 z) { f32x4 r; r[0] = z[0] * fast_sigmoid(z[0]); r[1] = z[1] * fast_sigmoid(z[1]); r[2] = z[2] * fast_sigmoid(z[2]); r[3] = z[3] * fast_sigmoid(z[3]); return r; }
; __device__ __forceinline__ f32x4 sigm4(const f32x4 z) { f32x4 r; r[0] = fast_sigmoid(z[0]); r[1] = fast_sigmoid(z[1]); r[2] = fast_sigmoid(z[2]); r[3] = fast_sigmoid(z[3]); return r; }
; __device__ __forceinline__ u32x2 pk4(const f32x4 v) { u32x2 w; w.x = pk2(v[0], v[1]); w.y = pk2(v[2], v[3]); return w; }
;     __device__ __forceinline__ void operator()(const AccT& acc, const Unit& u, int wr, int wc, int fr, int fq) const {
;     ...
;                     float* vo = (row < MP ? vp + (size_t)row * DM : vs + (size_t)(row - MP) * DM) + colt;
;     ...
;                     for (int bj = 0; bj < 2; ++bj) {
;                         f32x4 v0 = acc[ai][bj][m][0], v1 = acc[ai][bj][m][1];
;                         if (vok) { __builtin_nontemporal_store(v0, (f32x4*)(vo + bj * 128)); __builtin_nontemporal_store(v1, (f32x4*)(vo + bj * 128 + 4)); }
;                         if (grp == 1) { v0 = silu4(v0); v1 = silu4(v1); } else if (grp >= 2) { v0 = sigm4(v0); v1 = sigm4(v1); }
;                         const u32x2 p0 = pk4(v0), p1 = pk4(v1); const u32x4 pw = {p0.x, p0.y, p1.x, p1.y};
;                         *(u32x4*)(O + (size_t)row * DM + bj * 128) = pw;
.LBB0_874:
	s_movk_i32 s8, 0x7f9f
	v_cvt_pk_bf16_f32 v148, v148, v149
	v_cvt_pk_bf16_f32 v149, v150, v151
	v_cvt_pk_bf16_f32 v150, v152, v153
	v_cvt_pk_bf16_f32 v151, v154, v155
	global_store_dwordx4 v[146:147], v[148:151], off offset:256 nt
	v_add_u32_e32 v146, 0xa0, v170
	v_cmp_lt_i32_e32 vcc, s8, v170
	s_and_saveexec_b64 s[20:21], vcc
	s_xor_b64 s[20:21], exec, s[20:21]
	s_cbranch_execz .LBB0_876
	v_add_u32_e32 v148, 0xffff8060, v170
	v_mov_b32_e32 v149, v181
	v_readlane_b32 s22, v252, 38
	v_lshlrev_b64 v[148:149], 12, v[148:149]
	v_readlane_b32 s23, v252, 39
	v_mov_b32_e32 v147, v181
	s_nop 0
	v_lshl_add_u64 v[148:149], s[22:23], 0, v[148:149]

; __device__ __forceinline__ f32x4 silu4(const f32x4 z) { f32x4 r; r[0] = z[0] * fast_sigmoid(z[0]); r[1] = z[1] * fast_sigmoid(z[1]); r[2] = z[2] * fast_sigmoid(z[2]); r[3] = z[3] * fast_sigmoid(z[3]); return r; }
; __device__ __forceinline__ f32x4 sigm4(const f32x4 z) { f32x4 r; r[0] = fast_sigmoid(z[0]); r[1] = fast_sigmoid(z[1]); r[2] = fast_sigmoid(z[2]); r[3] = fast_sigmoid(z[3]); return r; }
; __device__ __forceinline__ u32x2 pk4(const f32x4 v) { u32x2 w; w.x = pk2(v[0], v[1]); w.y = pk2(v[2], v[3]); return w; }
;     __device__ __forceinline__ void operator()(const AccT& acc, const Unit& u, int wr, int wc, int fr, int fq) const {
;     ...
;                     const int row = row0 + ai * 128 + m * 16;
;                     float* vo = (row < MP ? vp + (size_t)row * DM : vs + (size_t)(row - MP) * DM) + colt;
;                     const bool vok = (grp == 0) && (row < MV);
; #pragma unroll
;                     for (int bj = 0; bj < 2; ++bj) {
;                         f32x4 v0 = acc[ai][bj][m][0], v1 = acc[ai][bj][m][1];
;                         if (vok) { __builtin_nontemporal_store(v0, (f32x4*)(vo + bj * 128)); __builtin_nontemporal_store(v1, (f32x4*)(vo + bj * 128 + 4)); }
;                         if (grp == 1) { v0 = silu4(v0); v1 = silu4(v1); } else if (grp >= 2) { v0 = sigm4(v0); v1 = sigm4(v1); }
;                         const u32x2 p0 = pk4(v0), p1 = pk4(v1); const u32x4 pw = {p0.x, p0.y, p1.x, p1.y};
;                         *(u32x4*)(O + (size_t)row * DM + bj * 128) = pw;
.LBB0_886:
	v_lshlrev_b64 v[146:147], 11, v[146:147]
	v_lshl_add_u64 v[146:147], v[144:145], 0, v[146:147]
	v_cvt_pk_bf16_f32 v150, v150, v151
	v_cvt_pk_bf16_f32 v151, v152, v153
	v_cvt_pk_bf16_f32 v152, v154, v155
	v_cvt_pk_bf16_f32 v153, v172, v173
	global_store_dwordx4 v[146:147], v[150:153], off nt
	s_and_saveexec_b64 s[22:23], s[20:21]
	s_cbranch_execz .LBB0_888
	global_store_dwordx4 v[148:149], v[40:43], off offset:512 nt
	global_store_dwordx4 v[148:149], v[32:35], off offset:528 nt

; __device__ __forceinline__ f32x4 silu4(const f32x4 z) { f32x4 r; r[0] = z[0] * fast_sigmoid(z[0]); r[1] = z[1] * fast_sigmoid(z[1]); r[2] = z[2] * fast_sigmoid(z[2]); r[3] = z[3] * fast_sigmoid(z[3]); return r; }
; __device__ __forceinline__ f32x4 sigm4(const f32x4 z) { f32x4 r; r[0] = fast_sigmoid(z[0]); r[1] = fast_sigmoid(z[1]); r[2] = fast_sigmoid(z[2]); r[3] = fast_sigmoid(z[3]); return r; }
; __device__ __forceinline__ u32x2 pk4(const f32x4 v) { u32x2 w; w.x = pk2(v[0], v[1]); w.y = pk2(v[2], v[3]); return w; }
;     __device__ __forceinline__ void operator()(const AccT& acc, const Unit& u, int wr, int wc, int fr, int fq) const {
;     ...
;                     float* vo = (row < MP ? vp + (size_t)row * DM : vs + (size_t)(row - MP) * DM) + colt;
;     ...
;                     for (int bj = 0; bj < 2; ++bj) {
;                         f32x4 v0 = acc[ai][bj][m][0], v1 = acc[ai][bj][m][1];
;                         if (vok) { __builtin_nontemporal_store(v0, (f32x4*)(vo + bj * 128)); __builtin_nontemporal_store(v1, (f32x4*)(vo + bj * 128 + 4)); }
;                         if (grp == 1) { v0 = silu4(v0); v1 = silu4(v1); } else if (grp >= 2) { v0 = sigm4(v0); v1 = sigm4(v1); }
;                         const u32x2 p0 = pk4(v0), p1 = pk4(v1); const u32x4 pw = {p0.x, p0.y, p1.x, p1.y};
;                         *(u32x4*)(O + (size_t)row * DM + bj * 128) = pw;
.LBB0_894:
	s_movk_i32 s8, 0x7f8f
	v_cvt_pk_bf16_f32 v148, v148, v149
	v_cvt_pk_bf16_f32 v149, v150, v151
	v_cvt_pk_bf16_f32 v150, v152, v153
	v_cvt_pk_bf16_f32 v151, v154, v155
	global_store_dwordx4 v[146:147], v[148:151], off offset:256 nt
	v_add_u32_e32 v146, 0xb0, v170
	v_cmp_lt_i32_e32 vcc, s8, v170
	s_and_saveexec_b64 s[20:21], vcc
	s_xor_b64 s[20:21], exec, s[20:21]
	s_cbranch_execz .LBB0_896
	v_add_u32_e32 v148, 0xffff8070, v170
	v_mov_b32_e32 v149, v181
	v_readlane_b32 s22, v252, 38
	v_lshlrev_b64 v[148:149], 12, v[148:149]
	v_readlane_b32 s23, v252, 39
	v_mov_b32_e32 v147, v181
	s_nop 0
	v_lshl_add_u64 v[148:149], s[22:23], 0, v[148:149]

; __device__ __forceinline__ f32x4 silu4(const f32x4 z) { f32x4 r; r[0] = z[0] * fast_sigmoid(z[0]); r[1] = z[1] * fast_sigmoid(z[1]); r[2] = z[2] * fast_sigmoid(z[2]); r[3] = z[3] * fast_sigmoid(z[3]); return r; }
; __device__ __forceinline__ f32x4 sigm4(const f32x4 z) { f32x4 r; r[0] = fast_sigmoid(z[0]); r[1] = fast_sigmoid(z[1]); r[2] = fast_sigmoid(z[2]); r[3] = fast_sigmoid(z[3]); return r; }
; __device__ __forceinline__ u32x2 pk4(const f32x4 v) { u32x2 w; w.x = pk2(v[0], v[1]); w.y = pk2(v[2], v[3]); return w; }
;     __device__ __forceinline__ void operator()(const AccT& acc, const Unit& u, int wr, int wc, int fr, int fq) const {
;     ...
;                     const int row = row0 + ai * 128 + m * 16;
;                     float* vo = (row < MP ? vp + (size_t)row * DM : vs + (size_t)(row - MP) * DM) + colt;
;                     const bool vok = (grp == 0) && (row < MV);
; #pragma unroll
;                     for (int bj = 0; bj < 2; ++bj) {
;                         f32x4 v0 = acc[ai][bj][m][0], v1 = acc[ai][bj][m][1];
;                         if (vok) { __builtin_nontemporal_store(v0, (f32x4*)(vo + bj * 128)); __builtin_nontemporal_store(v1, (f32x4*)(vo + bj * 128 + 4)); }
;                         if (grp == 1) { v0 = silu4(v0); v1 = silu4(v1); } else if (grp >= 2) { v0 = sigm4(v0); v1 = sigm4(v1); }
;                         const u32x2 p0 = pk4(v0), p1 = pk4(v1); const u32x4 pw = {p0.x, p0.y, p1.x, p1.y};
;                         *(u32x4*)(O + (size_t)row * DM + bj * 128) = pw;
.LBB0_906:
	v_lshlrev_b64 v[146:147], 11, v[146:147]
	v_lshl_add_u64 v[144:145], v[144:145], 0, v[146:147]
	v_cvt_pk_bf16_f32 v150, v150, v151
	v_cvt_pk_bf16_f32 v151, v152, v153
	v_cvt_pk_bf16_f32 v152, v154, v155
	v_cvt_pk_bf16_f32 v153, v172, v173
	global_store_dwordx4 v[144:145], v[150:153], off nt
	s_and_saveexec_b64 s[20:21], s[0:1]
	s_cbranch_execz .LBB0_908
	global_store_dwordx4 v[148:149], v[24:27], off offset:512 nt
	global_store_dwordx4 v[148:149], v[16:19], off offset:528 nt

; __device__ __forceinline__ f32x4 silu4(const f32x4 z) { f32x4 r; r[0] = z[0] * fast_sigmoid(z[0]); r[1] = z[1] * fast_sigmoid(z[1]); r[2] = z[2] * fast_sigmoid(z[2]); r[3] = z[3] * fast_sigmoid(z[3]); return r; }
; __device__ __forceinline__ f32x4 sigm4(const f32x4 z) { f32x4 r; r[0] = fast_sigmoid(z[0]); r[1] = fast_sigmoid(z[1]); r[2] = fast_sigmoid(z[2]); r[3] = fast_sigmoid(z[3]); return r; }
; __device__ __forceinline__ u32x2 pk4(const f32x4 v) { u32x2 w; w.x = pk2(v[0], v[1]); w.y = pk2(v[2], v[3]); return w; }
;     __device__ __forceinline__ void operator()(const AccT& acc, const Unit& u, int wr, int wc, int fr, int fq) const {
;     ...
;                     for (int bj = 0; bj < 2; ++bj) {
;                         f32x4 v0 = acc[ai][bj][m][0], v1 = acc[ai][bj][m][1];
;                         if (vok) { __builtin_nontemporal_store(v0, (f32x4*)(vo + bj * 128)); __builtin_nontemporal_store(v1, (f32x4*)(vo + bj * 128 + 4)); }
;                         if (grp == 1) { v0 = silu4(v0); v1 = silu4(v1); } else if (grp >= 2) { v0 = sigm4(v0); v1 = sigm4(v1); }
;                         const u32x2 p0 = pk4(v0), p1 = pk4(v1); const u32x4 pw = {p0.x, p0.y, p1.x, p1.y};
;                         *(u32x4*)(O + (size_t)row * DM + bj * 128) = pw;
.LBB0_914:
	v_cvt_pk_bf16_f32 v146, v146, v147
	v_cvt_pk_bf16_f32 v147, v148, v149
	s_nop 0
	v_cvt_pk_bf16_f32 v148, v152, v153
	v_cvt_pk_bf16_f32 v149, v150, v151
	global_store_dwordx4 v[144:145], v[146:149], off offset:256 nt
	s_mov_b64 s[0:1], 0

; #define LAS __attribute__((address_space(3)))
; __device__ __forceinline__ size_t ksw_off(int sblk, int hd) { return ((size_t)sblk * NHEAD + hd) * 4096; }
; __device__ __forceinline__ u32x2 pk4(const f32x4 v) { u32x2 w; w.x = pk2(v[0], v[1]); w.y = pk2(v[2], v[3]); return w; }
;     __device__ __forceinline__ void operator()(const AccT& acc, const Unit& u, int wr, int wc, int fr, int fq) const {
;     ...
;             asm volatile("s_waitcnt lgkmcnt(0)" ::: "memory"); __builtin_amdgcn_s_barrier(); asm volatile("" ::: "memory");
;             const float* gp = (isk ? kg : qg) + wc * 32 + 8 * fq;
;             f32x4 gv[2]; gv[0] = *(const f32x4*)gp; gv[1] = *(const f32x4*)(gp + 4);
;             if (!isk) { gv[0] *= QSCALE; gv[1] *= QSCALE; }
;             bf16_t* O = PA + (size_t)(isk ? 3 : 2) * MPAD * DM + colt;
; #pragma unroll
;             for (int ai = 0; ai < 2; ++ai)
; #pragma unroll
;                 for (int m = 0; m < 4; ++m) {
;                     const int row = row0 + ai * 128 + m * 16;
;                     float* ko = (row < MP ? kp + (size_t)row * DM : ks + (size_t)(row - MP) * DM) + colt;
;                     const bool kok = isk && row < MV;
;                     int sblk, kr;
;                     if (row < MP) { const int b = row / TP, t = row - b * TP; sblk = b * NGRP_ + (t >> 5); kr = t & 31; } else { const int q = row - MP; sblk = NBP * NGRP_ + (q >> 4); kr = q & 15; }
; #pragma unroll
;                     for (int bj = 0; bj < 2; ++bj) {
;                         const f32x4 t = *(const LAS f32x4*)(xs + ((((wr * 2 + ai) * 4 + m) * 2 + bj) * 16 + fr) * 4);
;                         const float rn = 1.0f / sqrtf(((t[0] + t[1]) + (t[2] + t[3])) * (1.f / HD) + EPS);
;                         const f32x4 v0 = acc[ai][bj][m][0] * rn * gv[0], v1 = acc[ai][bj][m][1] * rn * gv[1];
;                         const u32x2 p0 = pk4(v0), p1 = pk4(v1); const u32x4 pw = {p0.x, p0.y, p1.x, p1.y};
;                         if (!isk) *(u32x4*)(O + (size_t)row * DM + bj * 128) = pw;
;                         else if (kok) { *(u32x4*)(ksw + ksw_off(sblk, 2 * (pn & 3) + bj) + ((2 * wc + (fq >> 1)) * 64 + kr + 32 * (fq & 1)) * 8) = pw;
;                             __builtin_nontemporal_store(v0, (f32x4*)(ko + bj * 128)); __builtin_nontemporal_store(v1, (f32x4*)(ko + bj * 128 + 4)); }
.LBB0_948:
	s_or_b64 exec, exec, s[0:1]
	s_cmp_gt_u32 s58, 19
	s_cselect_b64 s[40:41], -1, 0
	s_cmp_lt_u32 s58, 20
	v_readlane_b32 s64, v252, 40
	s_cselect_b64 s[20:21], -1, 0
	s_and_b64 s[0:1], s[40:41], exec
	v_readlane_b32 s66, v252, 42
	v_readlane_b32 s68, v252, 44
	v_readlane_b32 s67, v252, 43
	v_readlane_b32 s69, v252, 45
	s_cselect_b32 s0, s68, s66
	s_cselect_b32 s1, s69, s67
	s_add_u32 s0, s0, s96
	s_waitcnt lgkmcnt(0)
	s_barrier
	s_addc_u32 s1, s1, 0
	s_waitcnt lgkmcnt(0)
	global_load_dwordx4 v[144:147], v204, s[0:1] offset:16
	global_load_dwordx4 v[148:151], v204, s[0:1]
	s_mov_b32 s0, 0x8040
	v_cmp_gt_i32_e64 s[0:1], s0, v170
	v_cmp_lt_i32_e32 vcc, s93, v170
	v_readlane_b32 s65, v252, 41
	v_readlane_b32 s70, v252, 46
	v_readlane_b32 s71, v252, 47
	v_readlane_b32 s72, v252, 48
	v_readlane_b32 s73, v252, 49
	v_readlane_b32 s74, v252, 50
	v_readlane_b32 s75, v252, 51
	v_readlane_b32 s76, v252, 52
	v_readlane_b32 s77, v252, 53
	v_readlane_b32 s78, v252, 54
	v_readlane_b32 s79, v252, 55
	s_and_saveexec_b64 s[22:23], vcc
	s_xor_b64 s[22:23], exec, s[22:23]
	s_add_i32 s8, s51, 0xffff7fc0
	s_lshr_b32 s8, s8, 4
	s_addk_i32 s8, 0x404
	s_or_saveexec_b64 s[22:23], s[22:23]
	v_mov_b32_e32 v194, s8
	v_mov_b32_e32 v205, v196
	s_xor_b64 exec, exec, s[22:23]
	v_mul_hi_i32 v152, v170, s82
	v_lshrrev_b32_e32 v153, 31, v152
	v_ashrrev_i32_e32 v152, 12, v152
	v_add_u32_e32 v152, v152, v153
	v_mad_i32_i24 v153, v152, s83, v170
	v_ashrrev_i32_e32 v154, 5, v153
	s_movk_i32 s8, 0x101
	v_mad_i32_i24 v194, v152, s8, v154
	v_and_b32_e32 v205, 31, v153
	s_or_b64 exec, exec, s[22:23]
	s_mov_b32 s22, 0x3e0293ee
	s_waitcnt vmcnt(0)
	v_pk_mul_f32 v[172:173], v[146:147], s[22:23] op_sel_hi:[1,0]
	v_pk_mul_f32 v[154:155], v[148:149], s[22:23] op_sel_hi:[1,0]
	v_cndmask_b32_e64 v172, v172, v146, s[40:41]
	v_add_u32_e32 v146, s92, v198
	v_cndmask_b32_e64 v177, v155, v149, s[40:41]
	v_cndmask_b32_e64 v176, v154, v148, s[40:41]
	v_cndmask_b32_e64 v173, v173, v147, s[40:41]
	ds_read_b128 v[146:149], v146
	s_and_b32 s8, s58, 3
	v_pk_mul_f32 v[178:179], v[144:145], s[22:23] op_sel_hi:[1,0]
	v_pk_mul_f32 v[152:153], v[150:151], s[22:23] op_sel_hi:[1,0]
	s_and_b64 s[22:23], s[40:41], exec
	v_cndmask_b32_e64 v179, v179, v145, s[40:41]
	v_cndmask_b32_e64 v178, v178, v144, s[40:41]
	s_waitcnt lgkmcnt(0)
	v_mov_b32_e32 v144, v147
	v_mov_b32_e32 v145, v148
	v_mov_b32_e32 v147, v149
	s_mov_b32 s22, 0xc300000
	v_pk_add_f32 v[144:145], v[144:145], v[146:147]
	s_cselect_b32 s22, s22, 0x8200000
	v_readlane_b32 s24, v254, 55
	v_add_f32_e32 v144, v144, v145
	s_add_u32 s22, s24, s22
	v_fmamk_f32 v144, v144, 0x3c000000, v212
	s_mov_b32 s24, 0xf800000
	v_mul_f32_e32 v145, 0x4f800000, v144
	v_cmp_gt_f32_e32 vcc, s24, v144
	v_lshl_or_b32 v192, s8, 8, v202
	v_readlane_b32 s25, v254, 56
	v_cndmask_b32_e32 v144, v144, v145, vcc
	v_sqrt_f32_e32 v145, v144
	s_addc_u32 s23, s25, 0
	v_lshlrev_b32_e32 v180, 1, v192
	v_lshl_add_u64 v[188:189], s[22:23], 0, v[180:181]
	v_add_u32_e32 v146, -1, v145
	v_fma_f32 v147, -v146, v145, v144
	v_cmp_ge_f32_e64 s[42:43], 0, v147
	v_add_u32_e32 v147, 1, v145
	v_ashrrev_i32_e32 v171, 31, v170
	v_cndmask_b32_e64 v146, v145, v146, s[42:43]
	v_fma_f32 v145, -v147, v145, v144
	v_cmp_lt_f32_e64 s[42:43], 0, v145
	v_cndmask_b32_e64 v175, v153, v151, s[40:41]
	v_cndmask_b32_e64 v174, v152, v150, s[40:41]
	v_cndmask_b32_e64 v145, v146, v147, s[42:43]
	v_mul_f32_e32 v146, 0x37800000, v145
	v_cndmask_b32_e32 v145, v145, v146, vcc
	v_cmp_class_f32_e32 vcc, v144, v213
	v_cndmask_b32_e64 v180, 0, 1, s[20:21]
	v_cmp_ne_u32_e64 s[42:43], 1, v180
	v_cndmask_b32_e32 v146, v145, v144, vcc
	v_div_scale_f32 v147, s[22:23], v146, v146, 1.0
	v_rcp_f32_e32 v148, v147
	v_lshlrev_b64 v[144:145], 11, v[170:171]
	v_lshl_add_u64 v[190:191], v[188:189], 0, v[144:145]
	s_mov_b32 s22, 0x8140
	v_fma_f32 v144, -v147, v148, 1.0
	v_fmac_f32_e32 v148, v144, v148
	v_div_scale_f32 v144, vcc, 1.0, v146, 1.0
	v_mul_f32_e32 v145, v144, v148
	v_fma_f32 v149, -v147, v145, v144
	v_fmac_f32_e32 v145, v149, v148
	v_fma_f32 v144, -v147, v145, v144
	v_div_fmas_f32 v144, v144, v148, v145
	v_div_fixup_f32 v148, v144, v146, 1.0
	v_pk_mul_f32 v[144:145], v[140:141], v[148:149] op_sel_hi:[1,0]
	v_pk_mul_f32 v[146:147], v[142:143], v[148:149] op_sel_hi:[1,0]
	v_pk_mul_f32 v[152:153], v[132:133], v[148:149] op_sel_hi:[1,0]
	v_pk_mul_f32 v[148:149], v[134:135], v[148:149] op_sel_hi:[1,0]
	v_cmp_gt_i32_e64 s[44:45], s22, v170
	v_pk_mul_f32 v[146:147], v[174:175], v[146:147]
	v_pk_mul_f32 v[144:145], v[176:177], v[144:145]
	v_pk_mul_f32 v[150:151], v[172:173], v[148:149]
	v_pk_mul_f32 v[148:149], v[178:179], v[152:153]
	s_andn2_b64 vcc, exec, s[20:21]
	s_mov_b64 s[22:23], -1
	v_cvt_pk_bf16_f32 v152, v144, v145
	v_cvt_pk_bf16_f32 v153, v146, v147
	v_cvt_pk_bf16_f32 v154, v148, v149
	v_cvt_pk_bf16_f32 v155, v150, v151
	s_cbranch_vccnz .LBB0_954
	s_mov_b64 s[22:23], 0
	global_store_dwordx4 v[190:191], v[152:155], off nt
.LBB0_954:
	s_lshl_b32 s24, s8, 13
	v_readlane_b32 s8, v252, 35
	v_add_u32_e32 v180, 0xffff7fc0, v170
	v_cndmask_b32_e64 v183, 0, v171, s[0:1]
	v_mov_b32_e32 v171, s8
	v_readlane_b32 s8, v252, 33
	v_cndmask_b32_e64 v182, v180, v170, s[0:1]
	v_lshlrev_b64 v[182:183], 12, v[182:183]
	v_mov_b32_e32 v180, s8
	v_readlane_b32 s8, v252, 34
	v_cndmask_b32_e64 v185, v171, v180, s[0:1]
	v_ashrrev_i32_e32 v195, 31, v194
	v_mov_b32_e32 v171, s8
	v_readlane_b32 s8, v252, 32
	s_and_b64 s[20:21], s[40:41], s[44:45]
	v_lshlrev_b64 v[194:195], 16, v[194:195]
	v_mov_b32_e32 v180, s8
	v_cndmask_b32_e64 v184, v171, v180, s[0:1]
	v_lshl_add_u64 v[182:183], v[184:185], 0, v[182:183]
	v_lshlrev_b32_e32 v180, 2, v192
	v_or_b32_e32 v171, v205, v199
	v_lshl_add_u64 v[192:193], v[182:183], 0, v[180:181]
	s_andn2_b64 vcc, exec, s[22:23]
	v_lshlrev_b32_e32 v171, 3, v171
	s_cbranch_vccnz .LBB0_958
	s_and_saveexec_b64 s[0:1], s[20:21]
	s_cbranch_execz .LBB0_957
	v_readlane_b32 s22, v252, 16
	v_readlane_b32 s23, v252, 17
	s_lshl_b32 s8, s24, 1
	v_lshlrev_b32_e32 v184, 1, v171
	v_lshl_add_u64 v[182:183], s[22:23], 0, v[194:195]
	v_lshl_add_u64 v[182:183], v[182:183], 0, s[8:9]
	v_mov_b32_e32 v185, v181
	v_lshl_add_u64 v[182:183], v[182:183], 0, v[184:185]
	global_store_dwordx4 v[182:183], v[152:155], off nt
	global_store_dwordx4 v[192:193], v[144:147], off nt
	global_store_dwordx4 v[192:193], v[148:151], off offset:16 nt

; #define LAS __attribute__((address_space(3)))
; __device__ __forceinline__ size_t ksw_off(int sblk, int hd) { return ((size_t)sblk * NHEAD + hd) * 4096; }
; __device__ __forceinline__ u32x2 pk4(const f32x4 v) { u32x2 w; w.x = pk2(v[0], v[1]); w.y = pk2(v[2], v[3]); return w; }
;     __device__ __forceinline__ void operator()(const AccT& acc, const Unit& u, int wr, int wc, int fr, int fq) const {
;     ...
;                         const f32x4 t = *(const LAS f32x4*)(xs + ((((wr * 2 + ai) * 4 + m) * 2 + bj) * 16 + fr) * 4);
;                         const float rn = 1.0f / sqrtf(((t[0] + t[1]) + (t[2] + t[3])) * (1.f / HD) + EPS);
;                         const f32x4 v0 = acc[ai][bj][m][0] * rn * gv[0], v1 = acc[ai][bj][m][1] * rn * gv[1];
;                         const u32x2 p0 = pk4(v0), p1 = pk4(v1); const u32x4 pw = {p0.x, p0.y, p1.x, p1.y};
;                         if (!isk) *(u32x4*)(O + (size_t)row * DM + bj * 128) = pw;
;                         else if (kok) { *(u32x4*)(ksw + ksw_off(sblk, 2 * (pn & 3) + bj) + ((2 * wc + (fq >> 1)) * 64 + kr + 32 * (fq & 1)) * 8) = pw;
;                             __builtin_nontemporal_store(v0, (f32x4*)(ko + bj * 128)); __builtin_nontemporal_store(v1, (f32x4*)(ko + bj * 128 + 4)); }
.LBB0_958:
	v_add_u32_e32 v144, s95, v198
	ds_read_b128 v[144:147], v144
	s_mov_b32 s0, 0xf800000
	s_waitcnt lgkmcnt(0)
	v_mov_b32_e32 v148, v145
	v_mov_b32_e32 v149, v146
	v_mov_b32_e32 v145, v147
	v_pk_add_f32 v[144:145], v[148:149], v[144:145]
	s_nop 0
	v_add_f32_e32 v144, v144, v145
	v_fmamk_f32 v144, v144, 0x3c000000, v212
	v_mul_f32_e32 v145, 0x4f800000, v144
	v_cmp_gt_f32_e32 vcc, s0, v144
	s_nop 1
	v_cndmask_b32_e32 v144, v144, v145, vcc
	v_sqrt_f32_e32 v145, v144
	s_nop 0
	v_add_u32_e32 v146, -1, v145
	v_add_u32_e32 v147, 1, v145
	v_fma_f32 v148, -v146, v145, v144
	v_fma_f32 v149, -v147, v145, v144
	v_cmp_ge_f32_e64 s[0:1], 0, v148
	s_nop 1
	v_cndmask_b32_e64 v145, v145, v146, s[0:1]
	v_cmp_lt_f32_e64 s[0:1], 0, v149
	s_nop 1
	v_cndmask_b32_e64 v145, v145, v147, s[0:1]
	v_mul_f32_e32 v146, 0x37800000, v145
	v_cndmask_b32_e32 v145, v145, v146, vcc
	v_cmp_class_f32_e32 vcc, v144, v213
	s_nop 1
	v_cndmask_b32_e32 v144, v145, v144, vcc
	v_div_scale_f32 v145, s[0:1], v144, v144, 1.0
	v_rcp_f32_e32 v146, v145
	s_mov_b64 s[0:1], -1
	v_fma_f32 v147, -v145, v146, 1.0
	v_fmac_f32_e32 v146, v147, v146
	v_div_scale_f32 v147, vcc, 1.0, v144, 1.0
	v_mul_f32_e32 v148, v147, v146
	v_fma_f32 v149, -v145, v148, v147
	v_fmac_f32_e32 v148, v149, v146
	v_fma_f32 v145, -v145, v148, v147
	v_div_fmas_f32 v145, v145, v146, v148
	v_div_fixup_f32 v148, v145, v144, 1.0
	v_pk_mul_f32 v[144:145], v[136:137], v[148:149] op_sel_hi:[1,0]
	v_pk_mul_f32 v[146:147], v[138:139], v[148:149] op_sel_hi:[1,0]
	v_pk_mul_f32 v[152:153], v[128:129], v[148:149] op_sel_hi:[1,0]
	v_pk_mul_f32 v[148:149], v[130:131], v[148:149] op_sel_hi:[1,0]
	v_pk_mul_f32 v[146:147], v[174:175], v[146:147]
	v_pk_mul_f32 v[144:145], v[176:177], v[144:145]
	v_pk_mul_f32 v[150:151], v[172:173], v[148:149]
	v_pk_mul_f32 v[148:149], v[178:179], v[152:153]
	s_and_b64 vcc, exec, s[42:43]
	v_cvt_pk_bf16_f32 v152, v144, v145
	v_cvt_pk_bf16_f32 v153, v146, v147
	v_cvt_pk_bf16_f32 v154, v148, v149
	v_cvt_pk_bf16_f32 v155, v150, v151
	s_cbranch_vccnz .LBB0_960
	s_mov_b64 s[0:1], 0
	global_store_dwordx4 v[190:191], v[152:155], off offset:256 nt
.LBB0_960:
	s_andn2_b64 vcc, exec, s[0:1]
	s_cbranch_vccnz .LBB0_964
	s_and_saveexec_b64 s[0:1], s[20:21]
	s_cbranch_execz .LBB0_963
	v_readlane_b32 s20, v252, 16
	v_readlane_b32 s21, v252, 17
	s_lshl_b32 s8, s24, 1
	v_lshlrev_b32_e32 v184, 1, v171
	v_lshl_add_u64 v[182:183], s[20:21], 0, v[194:195]
	v_lshl_add_u64 v[182:183], v[182:183], 0, s[8:9]
	v_mov_b32_e32 v185, v181
	v_lshl_add_u64 v[182:183], v[182:183], 0, v[184:185]
	v_add_co_u32_e32 v182, vcc, 0x2000, v182
	s_nop 1
	v_addc_co_u32_e32 v183, vcc, 0, v183, vcc
	global_store_dwordx4 v[182:183], v[152:155], off nt
	global_store_dwordx4 v[192:193], v[144:147], off offset:512 nt
	global_store_dwordx4 v[192:193], v[148:151], off offset:528 nt

; #define LAS __attribute__((address_space(3)))
; __device__ __forceinline__ size_t ksw_off(int sblk, int hd) { return ((size_t)sblk * NHEAD + hd) * 4096; }
; __device__ __forceinline__ u32x2 pk4(const f32x4 v) { u32x2 w; w.x = pk2(v[0], v[1]); w.y = pk2(v[2], v[3]); return w; }
;     __device__ __forceinline__ void operator()(const AccT& acc, const Unit& u, int wr, int wc, int fr, int fq) const {
;     ...
;                     const int row = row0 + ai * 128 + m * 16;
;                     float* ko = (row < MP ? kp + (size_t)row * DM : ks + (size_t)(row - MP) * DM) + colt;
;                     const bool kok = isk && row < MV;
;                     int sblk, kr;
;                     if (row < MP) { const int b = row / TP, t = row - b * TP; sblk = b * NGRP_ + (t >> 5); kr = t & 31; } else { const int q = row - MP; sblk = NBP * NGRP_ + (q >> 4); kr = q & 15; }
; #pragma unroll
;                     for (int bj = 0; bj < 2; ++bj) {
;                         const f32x4 t = *(const LAS f32x4*)(xs + ((((wr * 2 + ai) * 4 + m) * 2 + bj) * 16 + fr) * 4);
;                         const float rn = 1.0f / sqrtf(((t[0] + t[1]) + (t[2] + t[3])) * (1.f / HD) + EPS);
;                         const f32x4 v0 = acc[ai][bj][m][0] * rn * gv[0], v1 = acc[ai][bj][m][1] * rn * gv[1];
;                         const u32x2 p0 = pk4(v0), p1 = pk4(v1); const u32x4 pw = {p0.x, p0.y, p1.x, p1.y};
;                         if (!isk) *(u32x4*)(O + (size_t)row * DM + bj * 128) = pw;
;                         else if (kok) { *(u32x4*)(ksw + ksw_off(sblk, 2 * (pn & 3) + bj) + ((2 * wc + (fq >> 1)) * 64 + kr + 32 * (fq & 1)) * 8) = pw;
;                             __builtin_nontemporal_store(v0, (f32x4*)(ko + bj * 128)); __builtin_nontemporal_store(v1, (f32x4*)(ko + bj * 128 + 4)); }
.LBB0_964:
	v_or_b32_e32 v192, 16, v170
	s_mov_b32 s0, 0x8040
	v_cmp_gt_i32_e64 s[0:1], s0, v192
	v_cmp_lt_i32_e32 vcc, s93, v192
	s_and_saveexec_b64 s[20:21], vcc
	s_xor_b64 s[20:21], exec, s[20:21]
	s_add_i32 s8, s51, 0xffff7fd0
	s_lshr_b32 s8, s8, 4
	s_addk_i32 s8, 0x404
	s_or_saveexec_b64 s[20:21], s[20:21]
	v_ashrrev_i32_e32 v193, 31, v192
	v_mov_b32_e32 v194, s8
	v_mov_b32_e32 v171, v196
	s_xor_b64 exec, exec, s[20:21]
	v_mul_hi_i32 v144, v192, s82
	v_lshrrev_b32_e32 v145, 31, v144
	v_ashrrev_i32_e32 v144, 12, v144
	v_add_u32_e32 v144, v144, v145
	v_mad_i32_i24 v145, v144, s83, v192
	v_ashrrev_i32_e32 v146, 5, v145
	s_movk_i32 s8, 0x101
	v_mad_i32_i24 v194, v144, s8, v146
	v_and_b32_e32 v171, 31, v145
	s_or_b64 exec, exec, s[20:21]
	v_add_u32_e32 v144, s2, v200
	ds_read_b128 v[144:147], v144
	s_mov_b32 s8, 0xf800000
	s_mov_b64 s[22:23], -1
	s_waitcnt lgkmcnt(0)
	v_mov_b32_e32 v148, v145
	v_mov_b32_e32 v149, v146
	v_mov_b32_e32 v145, v147
	v_pk_add_f32 v[144:145], v[148:149], v[144:145]
	s_nop 0
	v_add_f32_e32 v144, v144, v145
	v_fmamk_f32 v144, v144, 0x3c000000, v212
	v_mul_f32_e32 v145, 0x4f800000, v144
	v_cmp_gt_f32_e32 vcc, s8, v144
	s_mov_b32 s8, 0x8140
	s_nop 0
	v_cndmask_b32_e32 v144, v144, v145, vcc
	v_sqrt_f32_e32 v145, v144
	s_nop 0
	v_add_u32_e32 v146, -1, v145
	v_add_u32_e32 v147, 1, v145
	v_fma_f32 v148, -v146, v145, v144
	v_fma_f32 v149, -v147, v145, v144
	v_cmp_ge_f32_e64 s[44:45], 0, v148
	s_nop 1
	v_cndmask_b32_e64 v145, v145, v146, s[44:45]
	v_cmp_lt_f32_e64 s[44:45], 0, v149
	s_nop 1
	v_cndmask_b32_e64 v145, v145, v147, s[44:45]
	v_mul_f32_e32 v146, 0x37800000, v145
	v_cndmask_b32_e32 v145, v145, v146, vcc
	v_cmp_class_f32_e32 vcc, v144, v213
	v_cmp_gt_i32_e64 s[44:45], s8, v192
	s_nop 0
	v_cndmask_b32_e32 v146, v145, v144, vcc
	v_div_scale_f32 v147, s[20:21], v146, v146, 1.0
	v_rcp_f32_e32 v148, v147
	v_lshlrev_b64 v[144:145], 11, v[192:193]
	v_lshl_add_u64 v[190:191], v[188:189], 0, v[144:145]
	v_fma_f32 v144, -v147, v148, 1.0
	v_fmac_f32_e32 v148, v144, v148
	v_div_scale_f32 v144, vcc, 1.0, v146, 1.0
	v_mul_f32_e32 v145, v144, v148
	v_fma_f32 v149, -v147, v145, v144
	v_fmac_f32_e32 v145, v149, v148
	v_fma_f32 v144, -v147, v145, v144
	v_div_fmas_f32 v144, v144, v148, v145
	v_div_fixup_f32 v148, v144, v146, 1.0
	v_pk_mul_f32 v[144:145], v[124:125], v[148:149] op_sel_hi:[1,0]
	v_pk_mul_f32 v[146:147], v[126:127], v[148:149] op_sel_hi:[1,0]
	v_pk_mul_f32 v[152:153], v[116:117], v[148:149] op_sel_hi:[1,0]
	v_pk_mul_f32 v[148:149], v[118:119], v[148:149] op_sel_hi:[1,0]
	v_pk_mul_f32 v[146:147], v[174:175], v[146:147]
	v_pk_mul_f32 v[144:145], v[176:177], v[144:145]
	v_pk_mul_f32 v[150:151], v[172:173], v[148:149]
	v_pk_mul_f32 v[148:149], v[178:179], v[152:153]
	s_and_b64 vcc, exec, s[42:43]
	v_cvt_pk_bf16_f32 v152, v144, v145
	v_cvt_pk_bf16_f32 v153, v146, v147
	v_cvt_pk_bf16_f32 v154, v148, v149
	v_cvt_pk_bf16_f32 v155, v150, v151
	s_cbranch_vccnz .LBB0_970
	s_mov_b64 s[22:23], 0
	global_store_dwordx4 v[190:191], v[152:155], off nt
.LBB0_970:
	v_readlane_b32 s8, v252, 35
	v_add_u32_e32 v182, 0xffff7fd0, v170
	v_cndmask_b32_e64 v183, 0, v193, s[0:1]
	v_mov_b32_e32 v184, s8
	v_readlane_b32 s8, v252, 33
	v_cndmask_b32_e64 v182, v182, v192, s[0:1]
	v_lshlrev_b64 v[182:183], 12, v[182:183]
	v_mov_b32_e32 v185, s8
	v_readlane_b32 s8, v252, 34
	v_cndmask_b32_e64 v185, v184, v185, s[0:1]
	v_ashrrev_i32_e32 v195, 31, v194
	v_mov_b32_e32 v184, s8
	v_readlane_b32 s8, v252, 32
	v_or_b32_e32 v171, v171, v199
	s_and_b64 s[20:21], s[40:41], s[44:45]
	v_mov_b32_e32 v192, s8
	v_cndmask_b32_e64 v184, v184, v192, s[0:1]
	v_lshl_add_u64 v[182:183], v[184:185], 0, v[182:183]
	v_lshl_add_u64 v[192:193], v[182:183], 0, v[180:181]
	v_lshlrev_b64 v[194:195], 16, v[194:195]
	s_andn2_b64 vcc, exec, s[22:23]
	v_lshlrev_b32_e32 v171, 3, v171
	s_cbranch_vccnz .LBB0_974
	s_and_saveexec_b64 s[0:1], s[20:21]
	s_cbranch_execz .LBB0_973
	v_readlane_b32 s22, v252, 16
	v_readlane_b32 s23, v252, 17
	s_lshl_b32 s8, s24, 1
	v_lshlrev_b32_e32 v184, 1, v171
	v_lshl_add_u64 v[182:183], s[22:23], 0, v[194:195]
	v_lshl_add_u64 v[182:183], v[182:183], 0, s[8:9]
	v_mov_b32_e32 v185, v181
	v_lshl_add_u64 v[182:183], v[182:183], 0, v[184:185]
	global_store_dwordx4 v[182:183], v[152:155], off nt
	global_store_dwordx4 v[192:193], v[144:147], off nt
	global_store_dwordx4 v[192:193], v[148:151], off offset:16 nt

; #define LAS __attribute__((address_space(3)))
; __device__ __forceinline__ u32x2 pk4(const f32x4 v) { u32x2 w; w.x = pk2(v[0], v[1]); w.y = pk2(v[2], v[3]); return w; }
;     __device__ __forceinline__ void operator()(const AccT& acc, const Unit& u, int wr, int wc, int fr, int fq) const {
;     ...
;                         const f32x4 t = *(const LAS f32x4*)(xs + ((((wr * 2 + ai) * 4 + m) * 2 + bj) * 16 + fr) * 4);
;                         const float rn = 1.0f / sqrtf(((t[0] + t[1]) + (t[2] + t[3])) * (1.f / HD) + EPS);
;                         const f32x4 v0 = acc[ai][bj][m][0] * rn * gv[0], v1 = acc[ai][bj][m][1] * rn * gv[1];
;                         const u32x2 p0 = pk4(v0), p1 = pk4(v1); const u32x4 pw = {p0.x, p0.y, p1.x, p1.y};
;                         if (!isk) *(u32x4*)(O + (size_t)row * DM + bj * 128) = pw;
.LBB0_974:
	v_add_u32_e32 v144, s2, v201
	ds_read_b128 v[144:147], v144
	s_mov_b32 s0, 0xf800000
	s_waitcnt lgkmcnt(0)
	v_mov_b32_e32 v148, v145
	v_mov_b32_e32 v149, v146
	v_mov_b32_e32 v145, v147
	v_pk_add_f32 v[144:145], v[148:149], v[144:145]
	s_nop 0
	v_add_f32_e32 v144, v144, v145
	v_fmamk_f32 v144, v144, 0x3c000000, v212
	v_mul_f32_e32 v145, 0x4f800000, v144
	v_cmp_gt_f32_e32 vcc, s0, v144
	s_nop 1
	v_cndmask_b32_e32 v144, v144, v145, vcc
	v_sqrt_f32_e32 v145, v144
	s_nop 0
	v_add_u32_e32 v146, -1, v145
	v_add_u32_e32 v147, 1, v145
	v_fma_f32 v148, -v146, v145, v144
	v_fma_f32 v149, -v147, v145, v144
	v_cmp_ge_f32_e64 s[0:1], 0, v148
	s_nop 1
	v_cndmask_b32_e64 v145, v145, v146, s[0:1]
	v_cmp_lt_f32_e64 s[0:1], 0, v149
	s_nop 1
	v_cndmask_b32_e64 v145, v145, v147, s[0:1]
	v_mul_f32_e32 v146, 0x37800000, v145
	v_cndmask_b32_e32 v145, v145, v146, vcc
	v_cmp_class_f32_e32 vcc, v144, v213
	s_nop 1
	v_cndmask_b32_e32 v144, v145, v144, vcc
	v_div_scale_f32 v145, s[0:1], v144, v144, 1.0
	v_rcp_f32_e32 v146, v145
	s_mov_b64 s[0:1], -1
	v_fma_f32 v147, -v145, v146, 1.0
	v_fmac_f32_e32 v146, v147, v146
	v_div_scale_f32 v147, vcc, 1.0, v144, 1.0
	v_mul_f32_e32 v148, v147, v146
	v_fma_f32 v149, -v145, v148, v147
	v_fmac_f32_e32 v148, v149, v146
	v_fma_f32 v145, -v145, v148, v147
	v_div_fmas_f32 v145, v145, v146, v148
	v_div_fixup_f32 v148, v145, v144, 1.0
	v_pk_mul_f32 v[144:145], v[120:121], v[148:149] op_sel_hi:[1,0]
	v_pk_mul_f32 v[146:147], v[122:123], v[148:149] op_sel_hi:[1,0]
	v_pk_mul_f32 v[152:153], v[112:113], v[148:149] op_sel_hi:[1,0]
	v_pk_mul_f32 v[148:149], v[114:115], v[148:149] op_sel_hi:[1,0]
	v_pk_mul_f32 v[146:147], v[174:175], v[146:147]
	v_pk_mul_f32 v[144:145], v[176:177], v[144:145]
	v_pk_mul_f32 v[150:151], v[172:173], v[148:149]
	v_pk_mul_f32 v[148:149], v[178:179], v[152:153]
	s_and_b64 vcc, exec, s[42:43]
	v_cvt_pk_bf16_f32 v152, v144, v145
	v_cvt_pk_bf16_f32 v153, v146, v147
	v_cvt_pk_bf16_f32 v154, v148, v149
	v_cvt_pk_bf16_f32 v155, v150, v151
	s_cbranch_vccnz .LBB0_976
	s_mov_b64 s[0:1], 0
	global_store_dwordx4 v[190:191], v[152:155], off offset:256 nt

; #define LAS __attribute__((address_space(3)))
; __device__ __forceinline__ size_t ksw_off(int sblk, int hd) { return ((size_t)sblk * NHEAD + hd) * 4096; }
; __device__ __forceinline__ u32x2 pk4(const f32x4 v) { u32x2 w; w.x = pk2(v[0], v[1]); w.y = pk2(v[2], v[3]); return w; }
;     __device__ __forceinline__ void operator()(const AccT& acc, const Unit& u, int wr, int wc, int fr, int fq) const {
;     ...
;                     const int row = row0 + ai * 128 + m * 16;
;                     float* ko = (row < MP ? kp + (size_t)row * DM : ks + (size_t)(row - MP) * DM) + colt;
;                     const bool kok = isk && row < MV;
;                     int sblk, kr;
;                     if (row < MP) { const int b = row / TP, t = row - b * TP; sblk = b * NGRP_ + (t >> 5); kr = t & 31; } else { const int q = row - MP; sblk = NBP * NGRP_ + (q >> 4); kr = q & 15; }
; #pragma unroll
;                     for (int bj = 0; bj < 2; ++bj) {
;                         const f32x4 t = *(const LAS f32x4*)(xs + ((((wr * 2 + ai) * 4 + m) * 2 + bj) * 16 + fr) * 4);
;                         const float rn = 1.0f / sqrtf(((t[0] + t[1]) + (t[2] + t[3])) * (1.f / HD) + EPS);
;                         const f32x4 v0 = acc[ai][bj][m][0] * rn * gv[0], v1 = acc[ai][bj][m][1] * rn * gv[1];
;                         const u32x2 p0 = pk4(v0), p1 = pk4(v1); const u32x4 pw = {p0.x, p0.y, p1.x, p1.y};
;                         if (!isk) *(u32x4*)(O + (size_t)row * DM + bj * 128) = pw;
;                         else if (kok) { *(u32x4*)(ksw + ksw_off(sblk, 2 * (pn & 3) + bj) + ((2 * wc + (fq >> 1)) * 64 + kr + 32 * (fq & 1)) * 8) = pw;
;                             __builtin_nontemporal_store(v0, (f32x4*)(ko + bj * 128)); __builtin_nontemporal_store(v1, (f32x4*)(ko + bj * 128 + 4)); }
.LBB0_980:
	v_or_b32_e32 v192, 32, v170
	s_mov_b32 s0, 0x8040
	v_cmp_gt_i32_e64 s[0:1], s0, v192
	v_cmp_lt_i32_e32 vcc, s93, v192
	s_and_saveexec_b64 s[20:21], vcc
	s_xor_b64 s[20:21], exec, s[20:21]
	s_add_i32 s8, s51, 0xffff7fe0
	s_lshr_b32 s8, s8, 4
	s_addk_i32 s8, 0x404
	s_or_saveexec_b64 s[20:21], s[20:21]
	v_ashrrev_i32_e32 v193, 31, v192
	v_mov_b32_e32 v194, s8
	v_mov_b32_e32 v171, v196
	s_xor_b64 exec, exec, s[20:21]
	v_mul_hi_i32 v144, v192, s82
	v_lshrrev_b32_e32 v145, 31, v144
	v_ashrrev_i32_e32 v144, 12, v144
	v_add_u32_e32 v144, v144, v145
	v_mad_i32_i24 v145, v144, s83, v192
	v_ashrrev_i32_e32 v146, 5, v145
	s_movk_i32 s8, 0x101
	v_mad_i32_i24 v194, v144, s8, v146
	v_and_b32_e32 v171, 31, v145
	s_or_b64 exec, exec, s[20:21]
	v_add_u32_e32 v144, s3, v200
	ds_read_b128 v[144:147], v144
	s_mov_b32 s8, 0xf800000
	s_mov_b64 s[22:23], -1
	s_waitcnt lgkmcnt(0)
	v_mov_b32_e32 v148, v145
	v_mov_b32_e32 v149, v146
	v_mov_b32_e32 v145, v147
	v_pk_add_f32 v[144:145], v[148:149], v[144:145]
	s_nop 0
	v_add_f32_e32 v144, v144, v145
	v_fmamk_f32 v144, v144, 0x3c000000, v212
	v_mul_f32_e32 v145, 0x4f800000, v144
	v_cmp_gt_f32_e32 vcc, s8, v144
	s_mov_b32 s8, 0x8140
	s_nop 0
	v_cndmask_b32_e32 v144, v144, v145, vcc
	v_sqrt_f32_e32 v145, v144
	s_nop 0
	v_add_u32_e32 v146, -1, v145
	v_add_u32_e32 v147, 1, v145
	v_fma_f32 v148, -v146, v145, v144
	v_fma_f32 v149, -v147, v145, v144
	v_cmp_ge_f32_e64 s[44:45], 0, v148
	s_nop 1
	v_cndmask_b32_e64 v145, v145, v146, s[44:45]
	v_cmp_lt_f32_e64 s[44:45], 0, v149
	s_nop 1
	v_cndmask_b32_e64 v145, v145, v147, s[44:45]
	v_mul_f32_e32 v146, 0x37800000, v145
	v_cndmask_b32_e32 v145, v145, v146, vcc
	v_cmp_class_f32_e32 vcc, v144, v213
	v_cmp_gt_i32_e64 s[44:45], s8, v192
	s_nop 0
	v_cndmask_b32_e32 v146, v145, v144, vcc
	v_div_scale_f32 v147, s[20:21], v146, v146, 1.0
	v_rcp_f32_e32 v148, v147
	v_lshlrev_b64 v[144:145], 11, v[192:193]
	v_lshl_add_u64 v[190:191], v[188:189], 0, v[144:145]
	v_fma_f32 v144, -v147, v148, 1.0
	v_fmac_f32_e32 v148, v144, v148
	v_div_scale_f32 v144, vcc, 1.0, v146, 1.0
	v_mul_f32_e32 v145, v144, v148
	v_fma_f32 v149, -v147, v145, v144
	v_fmac_f32_e32 v145, v149, v148
	v_fma_f32 v144, -v147, v145, v144
	v_div_fmas_f32 v144, v144, v148, v145
	v_div_fixup_f32 v148, v144, v146, 1.0
	v_pk_mul_f32 v[144:145], v[108:109], v[148:149] op_sel_hi:[1,0]
	v_pk_mul_f32 v[146:147], v[110:111], v[148:149] op_sel_hi:[1,0]
	v_pk_mul_f32 v[152:153], v[100:101], v[148:149] op_sel_hi:[1,0]
	v_pk_mul_f32 v[148:149], v[102:103], v[148:149] op_sel_hi:[1,0]
	v_pk_mul_f32 v[146:147], v[174:175], v[146:147]
	v_pk_mul_f32 v[144:145], v[176:177], v[144:145]
	v_pk_mul_f32 v[150:151], v[172:173], v[148:149]
	v_pk_mul_f32 v[148:149], v[178:179], v[152:153]
	s_and_b64 vcc, exec, s[42:43]
	v_cvt_pk_bf16_f32 v152, v144, v145
	v_cvt_pk_bf16_f32 v153, v146, v147
	v_cvt_pk_bf16_f32 v154, v148, v149
	v_cvt_pk_bf16_f32 v155, v150, v151
	s_cbranch_vccnz .LBB0_986
	s_mov_b64 s[22:23], 0
	global_store_dwordx4 v[190:191], v[152:155], off nt
.LBB0_986:
	v_readlane_b32 s8, v252, 35
	v_add_u32_e32 v182, 0xffff7fe0, v170
	v_cndmask_b32_e64 v183, 0, v193, s[0:1]
	v_mov_b32_e32 v184, s8
	v_readlane_b32 s8, v252, 33
	v_cndmask_b32_e64 v182, v182, v192, s[0:1]
	v_lshlrev_b64 v[182:183], 12, v[182:183]
	v_mov_b32_e32 v185, s8
	v_readlane_b32 s8, v252, 34
	v_cndmask_b32_e64 v185, v184, v185, s[0:1]
	v_ashrrev_i32_e32 v195, 31, v194
	v_mov_b32_e32 v184, s8
	v_readlane_b32 s8, v252, 32
	v_or_b32_e32 v171, v171, v199
	s_and_b64 s[20:21], s[40:41], s[44:45]
	v_mov_b32_e32 v192, s8
	v_cndmask_b32_e64 v184, v184, v192, s[0:1]
	v_lshl_add_u64 v[182:183], v[184:185], 0, v[182:183]
	v_lshl_add_u64 v[192:193], v[182:183], 0, v[180:181]
	v_lshlrev_b64 v[194:195], 16, v[194:195]
	s_andn2_b64 vcc, exec, s[22:23]
	v_lshlrev_b32_e32 v171, 3, v171
	s_cbranch_vccnz .LBB0_990
	s_and_saveexec_b64 s[0:1], s[20:21]
	s_cbranch_execz .LBB0_989
	v_readlane_b32 s22, v252, 16
	v_readlane_b32 s23, v252, 17
	s_lshl_b32 s8, s24, 1
	v_lshlrev_b32_e32 v184, 1, v171
	v_lshl_add_u64 v[182:183], s[22:23], 0, v[194:195]
	v_lshl_add_u64 v[182:183], v[182:183], 0, s[8:9]
	v_mov_b32_e32 v185, v181
	v_lshl_add_u64 v[182:183], v[182:183], 0, v[184:185]
	global_store_dwordx4 v[182:183], v[152:155], off nt
	global_store_dwordx4 v[192:193], v[144:147], off nt
	global_store_dwordx4 v[192:193], v[148:151], off offset:16 nt

; #define LAS __attribute__((address_space(3)))
; __device__ __forceinline__ u32x2 pk4(const f32x4 v) { u32x2 w; w.x = pk2(v[0], v[1]); w.y = pk2(v[2], v[3]); return w; }
;     __device__ __forceinline__ void operator()(const AccT& acc, const Unit& u, int wr, int wc, int fr, int fq) const {
;     ...
;                         const f32x4 t = *(const LAS f32x4*)(xs + ((((wr * 2 + ai) * 4 + m) * 2 + bj) * 16 + fr) * 4);
;                         const float rn = 1.0f / sqrtf(((t[0] + t[1]) + (t[2] + t[3])) * (1.f / HD) + EPS);
;                         const f32x4 v0 = acc[ai][bj][m][0] * rn * gv[0], v1 = acc[ai][bj][m][1] * rn * gv[1];
;                         const u32x2 p0 = pk4(v0), p1 = pk4(v1); const u32x4 pw = {p0.x, p0.y, p1.x, p1.y};
;                         if (!isk) *(u32x4*)(O + (size_t)row * DM + bj * 128) = pw;
.LBB0_990:
	v_add_u32_e32 v144, s3, v201
	ds_read_b128 v[144:147], v144
	s_mov_b32 s0, 0xf800000
	s_waitcnt lgkmcnt(0)
	v_mov_b32_e32 v148, v145
	v_mov_b32_e32 v149, v146
	v_mov_b32_e32 v145, v147
	v_pk_add_f32 v[144:145], v[148:149], v[144:145]
	s_nop 0
	v_add_f32_e32 v144, v144, v145
	v_fmamk_f32 v144, v144, 0x3c000000, v212
	v_mul_f32_e32 v145, 0x4f800000, v144
	v_cmp_gt_f32_e32 vcc, s0, v144
	s_nop 1
	v_cndmask_b32_e32 v144, v144, v145, vcc
	v_sqrt_f32_e32 v145, v144
	s_nop 0
	v_add_u32_e32 v146, -1, v145
	v_add_u32_e32 v147, 1, v145
	v_fma_f32 v148, -v146, v145, v144
	v_fma_f32 v149, -v147, v145, v144
	v_cmp_ge_f32_e64 s[0:1], 0, v148
	s_nop 1
	v_cndmask_b32_e64 v145, v145, v146, s[0:1]
	v_cmp_lt_f32_e64 s[0:1], 0, v149
	s_nop 1
	v_cndmask_b32_e64 v145, v145, v147, s[0:1]
	v_mul_f32_e32 v146, 0x37800000, v145
	v_cndmask_b32_e32 v145, v145, v146, vcc
	v_cmp_class_f32_e32 vcc, v144, v213
	s_nop 1
	v_cndmask_b32_e32 v144, v145, v144, vcc
	v_div_scale_f32 v145, s[0:1], v144, v144, 1.0
	v_rcp_f32_e32 v146, v145
	s_mov_b64 s[0:1], -1
	v_fma_f32 v147, -v145, v146, 1.0
	v_fmac_f32_e32 v146, v147, v146
	v_div_scale_f32 v147, vcc, 1.0, v144, 1.0
	v_mul_f32_e32 v148, v147, v146
	v_fma_f32 v149, -v145, v148, v147
	v_fmac_f32_e32 v148, v149, v146
	v_fma_f32 v145, -v145, v148, v147
	v_div_fmas_f32 v145, v145, v146, v148
	v_div_fixup_f32 v148, v145, v144, 1.0
	v_pk_mul_f32 v[144:145], v[104:105], v[148:149] op_sel_hi:[1,0]
	v_pk_mul_f32 v[146:147], v[106:107], v[148:149] op_sel_hi:[1,0]
	v_pk_mul_f32 v[152:153], v[96:97], v[148:149] op_sel_hi:[1,0]
	v_pk_mul_f32 v[148:149], v[98:99], v[148:149] op_sel_hi:[1,0]
	v_pk_mul_f32 v[146:147], v[174:175], v[146:147]
	v_pk_mul_f32 v[144:145], v[176:177], v[144:145]
	v_pk_mul_f32 v[150:151], v[172:173], v[148:149]
	v_pk_mul_f32 v[148:149], v[178:179], v[152:153]
	s_and_b64 vcc, exec, s[42:43]
	v_cvt_pk_bf16_f32 v152, v144, v145
	v_cvt_pk_bf16_f32 v153, v146, v147
	v_cvt_pk_bf16_f32 v154, v148, v149
	v_cvt_pk_bf16_f32 v155, v150, v151
	s_cbranch_vccnz .LBB0_992
	s_mov_b64 s[0:1], 0
	global_store_dwordx4 v[190:191], v[152:155], off offset:256 nt

; #define LAS __attribute__((address_space(3)))
; __device__ __forceinline__ size_t ksw_off(int sblk, int hd) { return ((size_t)sblk * NHEAD + hd) * 4096; }
; __device__ __forceinline__ u32x2 pk4(const f32x4 v) { u32x2 w; w.x = pk2(v[0], v[1]); w.y = pk2(v[2], v[3]); return w; }
;     __device__ __forceinline__ void operator()(const AccT& acc, const Unit& u, int wr, int wc, int fr, int fq) const {
;     ...
;                     const int row = row0 + ai * 128 + m * 16;
;                     float* ko = (row < MP ? kp + (size_t)row * DM : ks + (size_t)(row - MP) * DM) + colt;
;                     const bool kok = isk && row < MV;
;                     int sblk, kr;
;                     if (row < MP) { const int b = row / TP, t = row - b * TP; sblk = b * NGRP_ + (t >> 5); kr = t & 31; } else { const int q = row - MP; sblk = NBP * NGRP_ + (q >> 4); kr = q & 15; }
; #pragma unroll
;                     for (int bj = 0; bj < 2; ++bj) {
;                         const f32x4 t = *(const LAS f32x4*)(xs + ((((wr * 2 + ai) * 4 + m) * 2 + bj) * 16 + fr) * 4);
;                         const float rn = 1.0f / sqrtf(((t[0] + t[1]) + (t[2] + t[3])) * (1.f / HD) + EPS);
;                         const f32x4 v0 = acc[ai][bj][m][0] * rn * gv[0], v1 = acc[ai][bj][m][1] * rn * gv[1];
;                         const u32x2 p0 = pk4(v0), p1 = pk4(v1); const u32x4 pw = {p0.x, p0.y, p1.x, p1.y};
;                         if (!isk) *(u32x4*)(O + (size_t)row * DM + bj * 128) = pw;
;                         else if (kok) { *(u32x4*)(ksw + ksw_off(sblk, 2 * (pn & 3) + bj) + ((2 * wc + (fq >> 1)) * 64 + kr + 32 * (fq & 1)) * 8) = pw;
;                             __builtin_nontemporal_store(v0, (f32x4*)(ko + bj * 128)); __builtin_nontemporal_store(v1, (f32x4*)(ko + bj * 128 + 4)); }
.LBB0_996:
	v_or_b32_e32 v192, 48, v170
	s_mov_b32 s0, 0x8040
	v_cmp_gt_i32_e64 s[0:1], s0, v192
	v_cmp_lt_i32_e32 vcc, s93, v192
	s_and_saveexec_b64 s[20:21], vcc
	s_xor_b64 s[20:21], exec, s[20:21]
	s_add_i32 s8, s51, 0xffff7ff0
	s_lshr_b32 s8, s8, 4
	s_addk_i32 s8, 0x404
	s_or_saveexec_b64 s[20:21], s[20:21]
	v_ashrrev_i32_e32 v193, 31, v192
	v_mov_b32_e32 v194, s8
	v_mov_b32_e32 v171, v196
	s_xor_b64 exec, exec, s[20:21]
	v_mul_hi_i32 v144, v192, s82
	v_lshrrev_b32_e32 v145, 31, v144
	v_ashrrev_i32_e32 v144, 12, v144
	v_add_u32_e32 v144, v144, v145
	v_mad_i32_i24 v145, v144, s83, v192
	v_ashrrev_i32_e32 v146, 5, v145
	s_movk_i32 s8, 0x101
	v_mad_i32_i24 v194, v144, s8, v146
	v_and_b32_e32 v171, 31, v145
	s_or_b64 exec, exec, s[20:21]
	v_add_u32_e32 v144, s86, v200
	ds_read_b128 v[144:147], v144
	s_mov_b32 s8, 0xf800000
	s_mov_b64 s[22:23], -1
	s_waitcnt lgkmcnt(0)
	v_mov_b32_e32 v148, v145
	v_mov_b32_e32 v149, v146
	v_mov_b32_e32 v145, v147
	v_pk_add_f32 v[144:145], v[148:149], v[144:145]
	s_nop 0
	v_add_f32_e32 v144, v144, v145
	v_fmamk_f32 v144, v144, 0x3c000000, v212
	v_mul_f32_e32 v145, 0x4f800000, v144
	v_cmp_gt_f32_e32 vcc, s8, v144
	s_mov_b32 s8, 0x8140
	s_nop 0
	v_cndmask_b32_e32 v144, v144, v145, vcc
	v_sqrt_f32_e32 v145, v144
	s_nop 0
	v_add_u32_e32 v146, -1, v145
	v_add_u32_e32 v147, 1, v145
	v_fma_f32 v148, -v146, v145, v144
	v_fma_f32 v149, -v147, v145, v144
	v_cmp_ge_f32_e64 s[44:45], 0, v148
	s_nop 1
	v_cndmask_b32_e64 v145, v145, v146, s[44:45]
	v_cmp_lt_f32_e64 s[44:45], 0, v149
	s_nop 1
	v_cndmask_b32_e64 v145, v145, v147, s[44:45]
	v_mul_f32_e32 v146, 0x37800000, v145
	v_cndmask_b32_e32 v145, v145, v146, vcc
	v_cmp_class_f32_e32 vcc, v144, v213
	v_cmp_gt_i32_e64 s[44:45], s8, v192
	s_nop 0
	v_cndmask_b32_e32 v146, v145, v144, vcc
	v_div_scale_f32 v147, s[20:21], v146, v146, 1.0
	v_rcp_f32_e32 v148, v147
	v_lshlrev_b64 v[144:145], 11, v[192:193]
	v_lshl_add_u64 v[190:191], v[188:189], 0, v[144:145]
	v_fma_f32 v144, -v147, v148, 1.0
	v_fmac_f32_e32 v148, v144, v148
	v_div_scale_f32 v144, vcc, 1.0, v146, 1.0
	v_mul_f32_e32 v145, v144, v148
	v_fma_f32 v149, -v147, v145, v144
	v_fmac_f32_e32 v145, v149, v148
	v_fma_f32 v144, -v147, v145, v144
	v_div_fmas_f32 v144, v144, v148, v145
	v_div_fixup_f32 v148, v144, v146, 1.0
	v_pk_mul_f32 v[144:145], v[92:93], v[148:149] op_sel_hi:[1,0]
	v_pk_mul_f32 v[146:147], v[94:95], v[148:149] op_sel_hi:[1,0]
	v_pk_mul_f32 v[152:153], v[84:85], v[148:149] op_sel_hi:[1,0]
	v_pk_mul_f32 v[148:149], v[86:87], v[148:149] op_sel_hi:[1,0]
	v_pk_mul_f32 v[146:147], v[174:175], v[146:147]
	v_pk_mul_f32 v[144:145], v[176:177], v[144:145]
	v_pk_mul_f32 v[150:151], v[172:173], v[148:149]
	v_pk_mul_f32 v[148:149], v[178:179], v[152:153]
	s_and_b64 vcc, exec, s[42:43]
	v_cvt_pk_bf16_f32 v152, v144, v145
	v_cvt_pk_bf16_f32 v153, v146, v147
	v_cvt_pk_bf16_f32 v154, v148, v149
	v_cvt_pk_bf16_f32 v155, v150, v151
	s_cbranch_vccnz .LBB0_1002
	s_mov_b64 s[22:23], 0
	global_store_dwordx4 v[190:191], v[152:155], off nt
.LBB0_1002:
	v_readlane_b32 s8, v252, 35
	v_add_u32_e32 v182, 0xffff7ff0, v170
	v_cndmask_b32_e64 v183, 0, v193, s[0:1]
	v_mov_b32_e32 v184, s8
	v_readlane_b32 s8, v252, 33
	v_cndmask_b32_e64 v182, v182, v192, s[0:1]
	v_lshlrev_b64 v[182:183], 12, v[182:183]
	v_mov_b32_e32 v185, s8
	v_readlane_b32 s8, v252, 34
	v_cndmask_b32_e64 v185, v184, v185, s[0:1]
	v_ashrrev_i32_e32 v195, 31, v194
	v_mov_b32_e32 v184, s8
	v_readlane_b32 s8, v252, 32
	v_or_b32_e32 v171, v171, v199
	s_and_b64 s[20:21], s[40:41], s[44:45]
	v_mov_b32_e32 v192, s8
	v_cndmask_b32_e64 v184, v184, v192, s[0:1]
	v_lshl_add_u64 v[182:183], v[184:185], 0, v[182:183]
	v_lshl_add_u64 v[192:193], v[182:183], 0, v[180:181]
	v_lshlrev_b64 v[194:195], 16, v[194:195]
	s_andn2_b64 vcc, exec, s[22:23]
	v_lshlrev_b32_e32 v171, 3, v171
	s_cbranch_vccnz .LBB0_1006
	s_and_saveexec_b64 s[0:1], s[20:21]
	s_cbranch_execz .LBB0_1005
	v_readlane_b32 s22, v252, 16
	v_readlane_b32 s23, v252, 17
	s_lshl_b32 s8, s24, 1
	v_lshlrev_b32_e32 v184, 1, v171
	v_lshl_add_u64 v[182:183], s[22:23], 0, v[194:195]
	v_lshl_add_u64 v[182:183], v[182:183], 0, s[8:9]
	v_mov_b32_e32 v185, v181
	v_lshl_add_u64 v[182:183], v[182:183], 0, v[184:185]
	global_store_dwordx4 v[182:183], v[152:155], off nt
	global_store_dwordx4 v[192:193], v[144:147], off nt
	global_store_dwordx4 v[192:193], v[148:151], off offset:16 nt

; #define LAS __attribute__((address_space(3)))
; __device__ __forceinline__ u32x2 pk4(const f32x4 v) { u32x2 w; w.x = pk2(v[0], v[1]); w.y = pk2(v[2], v[3]); return w; }
;     __device__ __forceinline__ void operator()(const AccT& acc, const Unit& u, int wr, int wc, int fr, int fq) const {
;     ...
;                         const f32x4 t = *(const LAS f32x4*)(xs + ((((wr * 2 + ai) * 4 + m) * 2 + bj) * 16 + fr) * 4);
;                         const float rn = 1.0f / sqrtf(((t[0] + t[1]) + (t[2] + t[3])) * (1.f / HD) + EPS);
;                         const f32x4 v0 = acc[ai][bj][m][0] * rn * gv[0], v1 = acc[ai][bj][m][1] * rn * gv[1];
;                         const u32x2 p0 = pk4(v0), p1 = pk4(v1); const u32x4 pw = {p0.x, p0.y, p1.x, p1.y};
;                         if (!isk) *(u32x4*)(O + (size_t)row * DM + bj * 128) = pw;
.LBB0_1006:
	v_add_u32_e32 v144, s86, v201
	ds_read_b128 v[144:147], v144
	s_mov_b32 s0, 0xf800000
	s_waitcnt lgkmcnt(0)
	v_mov_b32_e32 v148, v145
	v_mov_b32_e32 v149, v146
	v_mov_b32_e32 v145, v147
	v_pk_add_f32 v[144:145], v[148:149], v[144:145]
	s_nop 0
	v_add_f32_e32 v144, v144, v145
	v_fmamk_f32 v144, v144, 0x3c000000, v212
	v_mul_f32_e32 v145, 0x4f800000, v144
	v_cmp_gt_f32_e32 vcc, s0, v144
	s_nop 1
	v_cndmask_b32_e32 v144, v144, v145, vcc
	v_sqrt_f32_e32 v145, v144
	s_nop 0
	v_add_u32_e32 v146, -1, v145
	v_add_u32_e32 v147, 1, v145
	v_fma_f32 v148, -v146, v145, v144
	v_fma_f32 v149, -v147, v145, v144
	v_cmp_ge_f32_e64 s[0:1], 0, v148
	s_nop 1
	v_cndmask_b32_e64 v145, v145, v146, s[0:1]
	v_cmp_lt_f32_e64 s[0:1], 0, v149
	s_nop 1
	v_cndmask_b32_e64 v145, v145, v147, s[0:1]
	v_mul_f32_e32 v146, 0x37800000, v145
	v_cndmask_b32_e32 v145, v145, v146, vcc
	v_cmp_class_f32_e32 vcc, v144, v213
	s_nop 1
	v_cndmask_b32_e32 v144, v145, v144, vcc
	v_div_scale_f32 v145, s[0:1], v144, v144, 1.0
	v_rcp_f32_e32 v146, v145
	s_mov_b64 s[0:1], -1
	v_fma_f32 v147, -v145, v146, 1.0
	v_fmac_f32_e32 v146, v147, v146
	v_div_scale_f32 v147, vcc, 1.0, v144, 1.0
	v_mul_f32_e32 v148, v147, v146
	v_fma_f32 v149, -v145, v148, v147
	v_fmac_f32_e32 v148, v149, v146
	v_fma_f32 v145, -v145, v148, v147
	v_div_fmas_f32 v145, v145, v146, v148
	v_div_fixup_f32 v148, v145, v144, 1.0
	v_pk_mul_f32 v[144:145], v[88:89], v[148:149] op_sel_hi:[1,0]
	v_pk_mul_f32 v[146:147], v[90:91], v[148:149] op_sel_hi:[1,0]
	v_pk_mul_f32 v[152:153], v[80:81], v[148:149] op_sel_hi:[1,0]
	v_pk_mul_f32 v[148:149], v[82:83], v[148:149] op_sel_hi:[1,0]
	v_pk_mul_f32 v[146:147], v[174:175], v[146:147]
	v_pk_mul_f32 v[144:145], v[176:177], v[144:145]
	v_pk_mul_f32 v[150:151], v[172:173], v[148:149]
	v_pk_mul_f32 v[148:149], v[178:179], v[152:153]
	s_and_b64 vcc, exec, s[42:43]
	v_cvt_pk_bf16_f32 v152, v144, v145
	v_cvt_pk_bf16_f32 v153, v146, v147
	v_cvt_pk_bf16_f32 v154, v148, v149
	v_cvt_pk_bf16_f32 v155, v150, v151
	s_cbranch_vccnz .LBB0_1008
	s_mov_b64 s[0:1], 0
	global_store_dwordx4 v[190:191], v[152:155], off offset:256 nt

; #define LAS __attribute__((address_space(3)))
; __device__ __forceinline__ size_t ksw_off(int sblk, int hd) { return ((size_t)sblk * NHEAD + hd) * 4096; }
; __device__ __forceinline__ u32x2 pk4(const f32x4 v) { u32x2 w; w.x = pk2(v[0], v[1]); w.y = pk2(v[2], v[3]); return w; }
;     __device__ __forceinline__ void operator()(const AccT& acc, const Unit& u, int wr, int wc, int fr, int fq) const {
;     ...
;                     const int row = row0 + ai * 128 + m * 16;
;                     float* ko = (row < MP ? kp + (size_t)row * DM : ks + (size_t)(row - MP) * DM) + colt;
;                     const bool kok = isk && row < MV;
;                     int sblk, kr;
;                     if (row < MP) { const int b = row / TP, t = row - b * TP; sblk = b * NGRP_ + (t >> 5); kr = t & 31; } else { const int q = row - MP; sblk = NBP * NGRP_ + (q >> 4); kr = q & 15; }
; #pragma unroll
;                     for (int bj = 0; bj < 2; ++bj) {
;                         const f32x4 t = *(const LAS f32x4*)(xs + ((((wr * 2 + ai) * 4 + m) * 2 + bj) * 16 + fr) * 4);
;                         const float rn = 1.0f / sqrtf(((t[0] + t[1]) + (t[2] + t[3])) * (1.f / HD) + EPS);
;                         const f32x4 v0 = acc[ai][bj][m][0] * rn * gv[0], v1 = acc[ai][bj][m][1] * rn * gv[1];
;                         const u32x2 p0 = pk4(v0), p1 = pk4(v1); const u32x4 pw = {p0.x, p0.y, p1.x, p1.y};
;                         if (!isk) *(u32x4*)(O + (size_t)row * DM + bj * 128) = pw;
;                         else if (kok) { *(u32x4*)(ksw + ksw_off(sblk, 2 * (pn & 3) + bj) + ((2 * wc + (fq >> 1)) * 64 + kr + 32 * (fq & 1)) * 8) = pw;
;                             __builtin_nontemporal_store(v0, (f32x4*)(ko + bj * 128)); __builtin_nontemporal_store(v1, (f32x4*)(ko + bj * 128 + 4)); }
.LBB0_1012:
	s_movk_i32 s0, 0x7fc0
	s_movk_i32 s8, 0x7fbf
	v_cmp_gt_i32_e64 s[0:1], s0, v170
	v_cmp_lt_i32_e32 vcc, s8, v170
	s_and_saveexec_b64 s[20:21], vcc
	s_xor_b64 s[20:21], exec, s[20:21]
	s_add_i32 s8, s51, 0xffff8040
	s_lshr_b32 s8, s8, 4
	s_addk_i32 s8, 0x404
	s_or_saveexec_b64 s[20:21], s[20:21]
	v_add_u32_e32 v192, 0x80, v170
	v_ashrrev_i32_e32 v193, 31, v192
	v_mov_b32_e32 v194, s8
	v_mov_b32_e32 v171, v196
	s_xor_b64 exec, exec, s[20:21]
	v_mul_hi_i32 v144, v192, s82
	v_lshrrev_b32_e32 v145, 31, v144
	v_ashrrev_i32_e32 v144, 12, v144
	v_add_u32_e32 v144, v144, v145
	v_mad_i32_i24 v145, v144, s83, v192
	v_ashrrev_i32_e32 v146, 5, v145
	s_movk_i32 s8, 0x101
	v_mad_i32_i24 v194, v144, s8, v146
	v_and_b32_e32 v171, 31, v145
	s_or_b64 exec, exec, s[20:21]
	v_add_u32_e32 v144, s85, v200
	ds_read_b128 v[144:147], v144
	s_mov_b32 s8, 0xf800000
	s_mov_b64 s[22:23], -1
	s_waitcnt lgkmcnt(0)
	v_mov_b32_e32 v148, v145
	v_mov_b32_e32 v149, v146
	v_mov_b32_e32 v145, v147
	v_pk_add_f32 v[144:145], v[148:149], v[144:145]
	s_nop 0
	v_add_f32_e32 v144, v144, v145
	v_fmamk_f32 v144, v144, 0x3c000000, v212
	v_mul_f32_e32 v145, 0x4f800000, v144
	v_cmp_gt_f32_e32 vcc, s8, v144
	s_mov_b32 s8, 0x80c0
	s_nop 0
	v_cndmask_b32_e32 v144, v144, v145, vcc
	v_sqrt_f32_e32 v145, v144
	s_nop 0
	v_add_u32_e32 v146, -1, v145
	v_add_u32_e32 v147, 1, v145
	v_fma_f32 v148, -v146, v145, v144
	v_fma_f32 v149, -v147, v145, v144
	v_cmp_ge_f32_e64 s[44:45], 0, v148
	s_nop 1
	v_cndmask_b32_e64 v145, v145, v146, s[44:45]
	v_cmp_lt_f32_e64 s[44:45], 0, v149
	s_nop 1
	v_cndmask_b32_e64 v145, v145, v147, s[44:45]
	v_mul_f32_e32 v146, 0x37800000, v145
	v_cndmask_b32_e32 v145, v145, v146, vcc
	v_cmp_class_f32_e32 vcc, v144, v213
	v_cmp_gt_i32_e64 s[44:45], s8, v170
	s_nop 0
	v_cndmask_b32_e32 v146, v145, v144, vcc
	v_div_scale_f32 v147, s[20:21], v146, v146, 1.0
	v_rcp_f32_e32 v148, v147
	v_lshlrev_b64 v[144:145], 11, v[192:193]
	v_lshl_add_u64 v[190:191], v[188:189], 0, v[144:145]
	v_fma_f32 v144, -v147, v148, 1.0
	v_fmac_f32_e32 v148, v144, v148
	v_div_scale_f32 v144, vcc, 1.0, v146, 1.0
	v_mul_f32_e32 v145, v144, v148
	v_fma_f32 v149, -v147, v145, v144
	v_fmac_f32_e32 v145, v149, v148
	v_fma_f32 v144, -v147, v145, v144
	v_div_fmas_f32 v144, v144, v148, v145
	v_div_fixup_f32 v148, v144, v146, 1.0
	v_pk_mul_f32 v[144:145], v[76:77], v[148:149] op_sel_hi:[1,0]
	v_pk_mul_f32 v[146:147], v[78:79], v[148:149] op_sel_hi:[1,0]
	v_pk_mul_f32 v[152:153], v[68:69], v[148:149] op_sel_hi:[1,0]
	v_pk_mul_f32 v[148:149], v[70:71], v[148:149] op_sel_hi:[1,0]
	v_pk_mul_f32 v[146:147], v[174:175], v[146:147]
	v_pk_mul_f32 v[144:145], v[176:177], v[144:145]
	v_pk_mul_f32 v[150:151], v[172:173], v[148:149]
	v_pk_mul_f32 v[148:149], v[178:179], v[152:153]
	s_and_b64 vcc, exec, s[42:43]
	v_cvt_pk_bf16_f32 v152, v144, v145
	v_cvt_pk_bf16_f32 v153, v146, v147
	v_cvt_pk_bf16_f32 v154, v148, v149
	v_cvt_pk_bf16_f32 v155, v150, v151
	s_cbranch_vccnz .LBB0_1018
	s_mov_b64 s[22:23], 0
	global_store_dwordx4 v[190:191], v[152:155], off nt
.LBB0_1018:
	v_readlane_b32 s8, v252, 35
	v_add_u32_e32 v182, 0xffff8040, v170
	v_cndmask_b32_e64 v183, 0, v193, s[0:1]
	v_mov_b32_e32 v184, s8
	v_readlane_b32 s8, v252, 33
	v_cndmask_b32_e64 v182, v182, v192, s[0:1]
	v_lshlrev_b64 v[182:183], 12, v[182:183]
	v_mov_b32_e32 v185, s8
	v_readlane_b32 s8, v252, 34
	v_cndmask_b32_e64 v185, v184, v185, s[0:1]
	v_ashrrev_i32_e32 v195, 31, v194
	v_mov_b32_e32 v184, s8
	v_readlane_b32 s8, v252, 32
	v_or_b32_e32 v171, v171, v199
	s_and_b64 s[20:21], s[40:41], s[44:45]
	v_mov_b32_e32 v192, s8
	v_cndmask_b32_e64 v184, v184, v192, s[0:1]
	v_lshl_add_u64 v[182:183], v[184:185], 0, v[182:183]
	v_lshl_add_u64 v[192:193], v[182:183], 0, v[180:181]
	v_lshlrev_b64 v[194:195], 16, v[194:195]
	s_andn2_b64 vcc, exec, s[22:23]
	v_lshlrev_b32_e32 v171, 3, v171
	s_cbranch_vccnz .LBB0_1022
	s_and_saveexec_b64 s[0:1], s[20:21]
	s_cbranch_execz .LBB0_1021
	v_readlane_b32 s22, v252, 16
	v_readlane_b32 s23, v252, 17
	s_lshl_b32 s8, s24, 1
	v_lshlrev_b32_e32 v184, 1, v171
	v_lshl_add_u64 v[182:183], s[22:23], 0, v[194:195]
	v_lshl_add_u64 v[182:183], v[182:183], 0, s[8:9]
	v_mov_b32_e32 v185, v181
	v_lshl_add_u64 v[182:183], v[182:183], 0, v[184:185]
	global_store_dwordx4 v[182:183], v[152:155], off nt
	global_store_dwordx4 v[192:193], v[144:147], off nt
	global_store_dwordx4 v[192:193], v[148:151], off offset:16 nt

; #define LAS __attribute__((address_space(3)))
; __device__ __forceinline__ u32x2 pk4(const f32x4 v) { u32x2 w; w.x = pk2(v[0], v[1]); w.y = pk2(v[2], v[3]); return w; }
;     __device__ __forceinline__ void operator()(const AccT& acc, const Unit& u, int wr, int wc, int fr, int fq) const {
;     ...
;                         const f32x4 t = *(const LAS f32x4*)(xs + ((((wr * 2 + ai) * 4 + m) * 2 + bj) * 16 + fr) * 4);
;                         const float rn = 1.0f / sqrtf(((t[0] + t[1]) + (t[2] + t[3])) * (1.f / HD) + EPS);
;                         const f32x4 v0 = acc[ai][bj][m][0] * rn * gv[0], v1 = acc[ai][bj][m][1] * rn * gv[1];
;                         const u32x2 p0 = pk4(v0), p1 = pk4(v1); const u32x4 pw = {p0.x, p0.y, p1.x, p1.y};
;                         if (!isk) *(u32x4*)(O + (size_t)row * DM + bj * 128) = pw;
.LBB0_1022:
	v_add_u32_e32 v144, s85, v201
	ds_read_b128 v[144:147], v144
	s_mov_b32 s0, 0xf800000
	s_waitcnt lgkmcnt(0)
	v_mov_b32_e32 v148, v145
	v_mov_b32_e32 v149, v146
	v_mov_b32_e32 v145, v147
	v_pk_add_f32 v[144:145], v[148:149], v[144:145]
	s_nop 0
	v_add_f32_e32 v144, v144, v145
	v_fmamk_f32 v144, v144, 0x3c000000, v212
	v_mul_f32_e32 v145, 0x4f800000, v144
	v_cmp_gt_f32_e32 vcc, s0, v144
	s_nop 1
	v_cndmask_b32_e32 v144, v144, v145, vcc
	v_sqrt_f32_e32 v145, v144
	s_nop 0
	v_add_u32_e32 v146, -1, v145
	v_add_u32_e32 v147, 1, v145
	v_fma_f32 v148, -v146, v145, v144
	v_fma_f32 v149, -v147, v145, v144
	v_cmp_ge_f32_e64 s[0:1], 0, v148
	s_nop 1
	v_cndmask_b32_e64 v145, v145, v146, s[0:1]
	v_cmp_lt_f32_e64 s[0:1], 0, v149
	s_nop 1
	v_cndmask_b32_e64 v145, v145, v147, s[0:1]
	v_mul_f32_e32 v146, 0x37800000, v145
	v_cndmask_b32_e32 v145, v145, v146, vcc
	v_cmp_class_f32_e32 vcc, v144, v213
	s_nop 1
	v_cndmask_b32_e32 v144, v145, v144, vcc
	v_div_scale_f32 v145, s[0:1], v144, v144, 1.0
	v_rcp_f32_e32 v146, v145
	s_mov_b64 s[0:1], -1
	v_fma_f32 v147, -v145, v146, 1.0
	v_fmac_f32_e32 v146, v147, v146
	v_div_scale_f32 v147, vcc, 1.0, v144, 1.0
	v_mul_f32_e32 v148, v147, v146
	v_fma_f32 v149, -v145, v148, v147
	v_fmac_f32_e32 v148, v149, v146
	v_fma_f32 v145, -v145, v148, v147
	v_div_fmas_f32 v145, v145, v146, v148
	v_div_fixup_f32 v148, v145, v144, 1.0
	v_pk_mul_f32 v[144:145], v[72:73], v[148:149] op_sel_hi:[1,0]
	v_pk_mul_f32 v[146:147], v[74:75], v[148:149] op_sel_hi:[1,0]
	v_pk_mul_f32 v[152:153], v[64:65], v[148:149] op_sel_hi:[1,0]
	v_pk_mul_f32 v[148:149], v[66:67], v[148:149] op_sel_hi:[1,0]
	v_pk_mul_f32 v[146:147], v[174:175], v[146:147]
	v_pk_mul_f32 v[144:145], v[176:177], v[144:145]
	v_pk_mul_f32 v[150:151], v[172:173], v[148:149]
	v_pk_mul_f32 v[148:149], v[178:179], v[152:153]
	s_and_b64 vcc, exec, s[42:43]
	v_cvt_pk_bf16_f32 v152, v144, v145
	v_cvt_pk_bf16_f32 v153, v146, v147
	v_cvt_pk_bf16_f32 v154, v148, v149
	v_cvt_pk_bf16_f32 v155, v150, v151
	s_cbranch_vccnz .LBB0_1024
	s_mov_b64 s[0:1], 0
	global_store_dwordx4 v[190:191], v[152:155], off offset:256 nt

; #define LAS __attribute__((address_space(3)))
; __device__ __forceinline__ size_t ksw_off(int sblk, int hd) { return ((size_t)sblk * NHEAD + hd) * 4096; }
; __device__ __forceinline__ u32x2 pk4(const f32x4 v) { u32x2 w; w.x = pk2(v[0], v[1]); w.y = pk2(v[2], v[3]); return w; }
;     __device__ __forceinline__ void operator()(const AccT& acc, const Unit& u, int wr, int wc, int fr, int fq) const {
;     ...
;                     const int row = row0 + ai * 128 + m * 16;
;                     float* ko = (row < MP ? kp + (size_t)row * DM : ks + (size_t)(row - MP) * DM) + colt;
;                     const bool kok = isk && row < MV;
;                     int sblk, kr;
;                     if (row < MP) { const int b = row / TP, t = row - b * TP; sblk = b * NGRP_ + (t >> 5); kr = t & 31; } else { const int q = row - MP; sblk = NBP * NGRP_ + (q >> 4); kr = q & 15; }
; #pragma unroll
;                     for (int bj = 0; bj < 2; ++bj) {
;                         const f32x4 t = *(const LAS f32x4*)(xs + ((((wr * 2 + ai) * 4 + m) * 2 + bj) * 16 + fr) * 4);
;                         const float rn = 1.0f / sqrtf(((t[0] + t[1]) + (t[2] + t[3])) * (1.f / HD) + EPS);
;                         const f32x4 v0 = acc[ai][bj][m][0] * rn * gv[0], v1 = acc[ai][bj][m][1] * rn * gv[1];
;                         const u32x2 p0 = pk4(v0), p1 = pk4(v1); const u32x4 pw = {p0.x, p0.y, p1.x, p1.y};
;                         if (!isk) *(u32x4*)(O + (size_t)row * DM + bj * 128) = pw;
;                         else if (kok) { *(u32x4*)(ksw + ksw_off(sblk, 2 * (pn & 3) + bj) + ((2 * wc + (fq >> 1)) * 64 + kr + 32 * (fq & 1)) * 8) = pw;
;                             __builtin_nontemporal_store(v0, (f32x4*)(ko + bj * 128)); __builtin_nontemporal_store(v1, (f32x4*)(ko + bj * 128 + 4)); }
.LBB0_1028:
	s_movk_i32 s0, 0x7fb0
	s_movk_i32 s8, 0x7faf
	v_cmp_gt_i32_e64 s[0:1], s0, v170
	v_cmp_lt_i32_e32 vcc, s8, v170
	s_and_saveexec_b64 s[20:21], vcc
	s_xor_b64 s[20:21], exec, s[20:21]
	s_add_i32 s8, s51, 0xffff8050
	s_lshr_b32 s8, s8, 4
	s_addk_i32 s8, 0x404
	s_or_saveexec_b64 s[20:21], s[20:21]
	v_add_u32_e32 v192, 0x90, v170
	v_ashrrev_i32_e32 v193, 31, v192
	v_mov_b32_e32 v194, s8
	v_mov_b32_e32 v171, v196
	s_xor_b64 exec, exec, s[20:21]
	v_mul_hi_i32 v144, v192, s82
	v_lshrrev_b32_e32 v145, 31, v144
	v_ashrrev_i32_e32 v144, 12, v144
	v_add_u32_e32 v144, v144, v145
	v_mad_i32_i24 v145, v144, s83, v192
	v_ashrrev_i32_e32 v146, 5, v145
	s_movk_i32 s8, 0x101
	v_mad_i32_i24 v194, v144, s8, v146
	v_and_b32_e32 v171, 31, v145
	s_or_b64 exec, exec, s[20:21]
	v_add_u32_e32 v144, s88, v200
	ds_read_b128 v[144:147], v144
	s_mov_b32 s8, 0xf800000
	s_mov_b64 s[22:23], -1
	s_waitcnt lgkmcnt(0)
	v_mov_b32_e32 v148, v145
	v_mov_b32_e32 v149, v146
	v_mov_b32_e32 v145, v147
	v_pk_add_f32 v[144:145], v[148:149], v[144:145]
	s_nop 0
	v_add_f32_e32 v144, v144, v145
	v_fmamk_f32 v144, v144, 0x3c000000, v212
	v_mul_f32_e32 v145, 0x4f800000, v144
	v_cmp_gt_f32_e32 vcc, s8, v144
	s_mov_b32 s8, 0x80b0
	s_nop 0
	v_cndmask_b32_e32 v144, v144, v145, vcc
	v_sqrt_f32_e32 v145, v144
	s_nop 0
	v_add_u32_e32 v146, -1, v145
	v_add_u32_e32 v147, 1, v145
	v_fma_f32 v148, -v146, v145, v144
	v_fma_f32 v149, -v147, v145, v144
	v_cmp_ge_f32_e64 s[44:45], 0, v148
	s_nop 1
	v_cndmask_b32_e64 v145, v145, v146, s[44:45]
	v_cmp_lt_f32_e64 s[44:45], 0, v149
	s_nop 1
	v_cndmask_b32_e64 v145, v145, v147, s[44:45]
	v_mul_f32_e32 v146, 0x37800000, v145
	v_cndmask_b32_e32 v145, v145, v146, vcc
	v_cmp_class_f32_e32 vcc, v144, v213
	v_cmp_gt_i32_e64 s[44:45], s8, v170
	s_nop 0
	v_cndmask_b32_e32 v146, v145, v144, vcc
	v_div_scale_f32 v147, s[20:21], v146, v146, 1.0
	v_rcp_f32_e32 v148, v147
	v_lshlrev_b64 v[144:145], 11, v[192:193]
	v_lshl_add_u64 v[190:191], v[188:189], 0, v[144:145]
	v_fma_f32 v144, -v147, v148, 1.0
	v_fmac_f32_e32 v148, v144, v148
	v_div_scale_f32 v144, vcc, 1.0, v146, 1.0
	v_mul_f32_e32 v145, v144, v148
	v_fma_f32 v149, -v147, v145, v144
	v_fmac_f32_e32 v145, v149, v148
	v_fma_f32 v144, -v147, v145, v144
	v_div_fmas_f32 v144, v144, v148, v145
	v_div_fixup_f32 v148, v144, v146, 1.0
	v_pk_mul_f32 v[144:145], v[60:61], v[148:149] op_sel_hi:[1,0]
	v_pk_mul_f32 v[146:147], v[62:63], v[148:149] op_sel_hi:[1,0]
	v_pk_mul_f32 v[152:153], v[52:53], v[148:149] op_sel_hi:[1,0]
	v_pk_mul_f32 v[148:149], v[54:55], v[148:149] op_sel_hi:[1,0]
	v_pk_mul_f32 v[146:147], v[174:175], v[146:147]
	v_pk_mul_f32 v[144:145], v[176:177], v[144:145]
	v_pk_mul_f32 v[150:151], v[172:173], v[148:149]
	v_pk_mul_f32 v[148:149], v[178:179], v[152:153]
	s_and_b64 vcc, exec, s[42:43]
	v_cvt_pk_bf16_f32 v152, v144, v145
	v_cvt_pk_bf16_f32 v153, v146, v147
	v_cvt_pk_bf16_f32 v154, v148, v149
	v_cvt_pk_bf16_f32 v155, v150, v151
	s_cbranch_vccnz .LBB0_1034
	s_mov_b64 s[22:23], 0
	global_store_dwordx4 v[190:191], v[152:155], off nt
.LBB0_1034:
	v_readlane_b32 s8, v252, 35
	v_add_u32_e32 v182, 0xffff8050, v170
	v_cndmask_b32_e64 v183, 0, v193, s[0:1]
	v_mov_b32_e32 v184, s8
	v_readlane_b32 s8, v252, 33
	v_cndmask_b32_e64 v182, v182, v192, s[0:1]
	v_lshlrev_b64 v[182:183], 12, v[182:183]
	v_mov_b32_e32 v185, s8
	v_readlane_b32 s8, v252, 34
	v_cndmask_b32_e64 v185, v184, v185, s[0:1]
	v_ashrrev_i32_e32 v195, 31, v194
	v_mov_b32_e32 v184, s8
	v_readlane_b32 s8, v252, 32
	v_or_b32_e32 v171, v171, v199
	s_and_b64 s[20:21], s[40:41], s[44:45]
	v_mov_b32_e32 v192, s8
	v_cndmask_b32_e64 v184, v184, v192, s[0:1]
	v_lshl_add_u64 v[182:183], v[184:185], 0, v[182:183]
	v_lshl_add_u64 v[192:193], v[182:183], 0, v[180:181]
	v_lshlrev_b64 v[194:195], 16, v[194:195]
	s_andn2_b64 vcc, exec, s[22:23]
	v_lshlrev_b32_e32 v171, 3, v171
	s_cbranch_vccnz .LBB0_1038
	s_and_saveexec_b64 s[0:1], s[20:21]
	s_cbranch_execz .LBB0_1037
	v_readlane_b32 s22, v252, 16
	v_readlane_b32 s23, v252, 17
	s_lshl_b32 s8, s24, 1
	v_lshlrev_b32_e32 v184, 1, v171
	v_lshl_add_u64 v[182:183], s[22:23], 0, v[194:195]
	v_lshl_add_u64 v[182:183], v[182:183], 0, s[8:9]
	v_mov_b32_e32 v185, v181
	v_lshl_add_u64 v[182:183], v[182:183], 0, v[184:185]
	global_store_dwordx4 v[182:183], v[152:155], off nt
	global_store_dwordx4 v[192:193], v[144:147], off nt
	global_store_dwordx4 v[192:193], v[148:151], off offset:16 nt

; #define LAS __attribute__((address_space(3)))
; __device__ __forceinline__ u32x2 pk4(const f32x4 v) { u32x2 w; w.x = pk2(v[0], v[1]); w.y = pk2(v[2], v[3]); return w; }
;     __device__ __forceinline__ void operator()(const AccT& acc, const Unit& u, int wr, int wc, int fr, int fq) const {
;     ...
;                         const f32x4 t = *(const LAS f32x4*)(xs + ((((wr * 2 + ai) * 4 + m) * 2 + bj) * 16 + fr) * 4);
;                         const float rn = 1.0f / sqrtf(((t[0] + t[1]) + (t[2] + t[3])) * (1.f / HD) + EPS);
;                         const f32x4 v0 = acc[ai][bj][m][0] * rn * gv[0], v1 = acc[ai][bj][m][1] * rn * gv[1];
;                         const u32x2 p0 = pk4(v0), p1 = pk4(v1); const u32x4 pw = {p0.x, p0.y, p1.x, p1.y};
;                         if (!isk) *(u32x4*)(O + (size_t)row * DM + bj * 128) = pw;
.LBB0_1038:
	v_add_u32_e32 v144, s88, v201
	ds_read_b128 v[144:147], v144
	s_mov_b32 s0, 0xf800000
	s_waitcnt lgkmcnt(0)
	v_mov_b32_e32 v148, v145
	v_mov_b32_e32 v149, v146
	v_mov_b32_e32 v145, v147
	v_pk_add_f32 v[144:145], v[148:149], v[144:145]
	s_nop 0
	v_add_f32_e32 v144, v144, v145
	v_fmamk_f32 v144, v144, 0x3c000000, v212
	v_mul_f32_e32 v145, 0x4f800000, v144
	v_cmp_gt_f32_e32 vcc, s0, v144
	s_nop 1
	v_cndmask_b32_e32 v144, v144, v145, vcc
	v_sqrt_f32_e32 v145, v144
	s_nop 0
	v_add_u32_e32 v146, -1, v145
	v_add_u32_e32 v147, 1, v145
	v_fma_f32 v148, -v146, v145, v144
	v_fma_f32 v149, -v147, v145, v144
	v_cmp_ge_f32_e64 s[0:1], 0, v148
	s_nop 1
	v_cndmask_b32_e64 v145, v145, v146, s[0:1]
	v_cmp_lt_f32_e64 s[0:1], 0, v149
	s_nop 1
	v_cndmask_b32_e64 v145, v145, v147, s[0:1]
	v_mul_f32_e32 v146, 0x37800000, v145
	v_cndmask_b32_e32 v145, v145, v146, vcc
	v_cmp_class_f32_e32 vcc, v144, v213
	s_nop 1
	v_cndmask_b32_e32 v144, v145, v144, vcc
	v_div_scale_f32 v145, s[0:1], v144, v144, 1.0
	v_rcp_f32_e32 v146, v145
	s_mov_b64 s[0:1], -1
	v_fma_f32 v147, -v145, v146, 1.0
	v_fmac_f32_e32 v146, v147, v146
	v_div_scale_f32 v147, vcc, 1.0, v144, 1.0
	v_mul_f32_e32 v148, v147, v146
	v_fma_f32 v149, -v145, v148, v147
	v_fmac_f32_e32 v148, v149, v146
	v_fma_f32 v145, -v145, v148, v147
	v_div_fmas_f32 v145, v145, v146, v148
	v_div_fixup_f32 v148, v145, v144, 1.0
	v_pk_mul_f32 v[144:145], v[56:57], v[148:149] op_sel_hi:[1,0]
	v_pk_mul_f32 v[146:147], v[58:59], v[148:149] op_sel_hi:[1,0]
	v_pk_mul_f32 v[152:153], v[48:49], v[148:149] op_sel_hi:[1,0]
	v_pk_mul_f32 v[148:149], v[50:51], v[148:149] op_sel_hi:[1,0]
	v_pk_mul_f32 v[146:147], v[174:175], v[146:147]
	v_pk_mul_f32 v[144:145], v[176:177], v[144:145]
	v_pk_mul_f32 v[150:151], v[172:173], v[148:149]
	v_pk_mul_f32 v[148:149], v[178:179], v[152:153]
	s_and_b64 vcc, exec, s[42:43]
	v_cvt_pk_bf16_f32 v152, v144, v145
	v_cvt_pk_bf16_f32 v153, v146, v147
	v_cvt_pk_bf16_f32 v154, v148, v149
	v_cvt_pk_bf16_f32 v155, v150, v151
	s_cbranch_vccnz .LBB0_1040
	s_mov_b64 s[0:1], 0
	global_store_dwordx4 v[190:191], v[152:155], off offset:256 nt

; #define LAS __attribute__((address_space(3)))
; __device__ __forceinline__ size_t ksw_off(int sblk, int hd) { return ((size_t)sblk * NHEAD + hd) * 4096; }
; __device__ __forceinline__ u32x2 pk4(const f32x4 v) { u32x2 w; w.x = pk2(v[0], v[1]); w.y = pk2(v[2], v[3]); return w; }
;     __device__ __forceinline__ void operator()(const AccT& acc, const Unit& u, int wr, int wc, int fr, int fq) const {
;     ...
;                     const int row = row0 + ai * 128 + m * 16;
;                     float* ko = (row < MP ? kp + (size_t)row * DM : ks + (size_t)(row - MP) * DM) + colt;
;                     const bool kok = isk && row < MV;
;                     int sblk, kr;
;                     if (row < MP) { const int b = row / TP, t = row - b * TP; sblk = b * NGRP_ + (t >> 5); kr = t & 31; } else { const int q = row - MP; sblk = NBP * NGRP_ + (q >> 4); kr = q & 15; }
; #pragma unroll
;                     for (int bj = 0; bj < 2; ++bj) {
;                         const f32x4 t = *(const LAS f32x4*)(xs + ((((wr * 2 + ai) * 4 + m) * 2 + bj) * 16 + fr) * 4);
;                         const float rn = 1.0f / sqrtf(((t[0] + t[1]) + (t[2] + t[3])) * (1.f / HD) + EPS);
;                         const f32x4 v0 = acc[ai][bj][m][0] * rn * gv[0], v1 = acc[ai][bj][m][1] * rn * gv[1];
;                         const u32x2 p0 = pk4(v0), p1 = pk4(v1); const u32x4 pw = {p0.x, p0.y, p1.x, p1.y};
;                         if (!isk) *(u32x4*)(O + (size_t)row * DM + bj * 128) = pw;
;                         else if (kok) { *(u32x4*)(ksw + ksw_off(sblk, 2 * (pn & 3) + bj) + ((2 * wc + (fq >> 1)) * 64 + kr + 32 * (fq & 1)) * 8) = pw;
;                             __builtin_nontemporal_store(v0, (f32x4*)(ko + bj * 128)); __builtin_nontemporal_store(v1, (f32x4*)(ko + bj * 128 + 4)); }
.LBB0_1044:
	s_movk_i32 s0, 0x7fa0
	s_movk_i32 s8, 0x7f9f
	v_cmp_gt_i32_e64 s[0:1], s0, v170
	v_cmp_lt_i32_e32 vcc, s8, v170
	s_and_saveexec_b64 s[20:21], vcc
	s_xor_b64 s[20:21], exec, s[20:21]
	s_add_i32 s8, s51, 0xffff8060
	s_lshr_b32 s8, s8, 4
	s_addk_i32 s8, 0x404
	s_or_saveexec_b64 s[20:21], s[20:21]
	v_add_u32_e32 v192, 0xa0, v170
	v_ashrrev_i32_e32 v193, 31, v192
	v_mov_b32_e32 v194, s8
	v_mov_b32_e32 v171, v196
	s_xor_b64 exec, exec, s[20:21]
	v_mul_hi_i32 v144, v192, s82
	v_lshrrev_b32_e32 v145, 31, v144
	v_ashrrev_i32_e32 v144, 12, v144
	v_add_u32_e32 v144, v144, v145
	v_mad_i32_i24 v145, v144, s83, v192
	v_ashrrev_i32_e32 v146, 5, v145
	s_movk_i32 s8, 0x101
	v_mad_i32_i24 v194, v144, s8, v146
	v_and_b32_e32 v171, 31, v145
	s_or_b64 exec, exec, s[20:21]
	v_add_u32_e32 v144, s89, v200
	ds_read_b128 v[144:147], v144
	s_mov_b32 s8, 0xf800000
	s_mov_b64 s[22:23], -1
	s_waitcnt lgkmcnt(0)
	v_mov_b32_e32 v148, v145
	v_mov_b32_e32 v149, v146
	v_mov_b32_e32 v145, v147
	v_pk_add_f32 v[144:145], v[148:149], v[144:145]
	s_nop 0
	v_add_f32_e32 v144, v144, v145
	v_fmamk_f32 v144, v144, 0x3c000000, v212
	v_mul_f32_e32 v145, 0x4f800000, v144
	v_cmp_gt_f32_e32 vcc, s8, v144
	s_mov_b32 s8, 0x80a0
	s_nop 0
	v_cndmask_b32_e32 v144, v144, v145, vcc
	v_sqrt_f32_e32 v145, v144
	s_nop 0
	v_add_u32_e32 v146, -1, v145
	v_add_u32_e32 v147, 1, v145
	v_fma_f32 v148, -v146, v145, v144
	v_fma_f32 v149, -v147, v145, v144
	v_cmp_ge_f32_e64 s[44:45], 0, v148
	s_nop 1
	v_cndmask_b32_e64 v145, v145, v146, s[44:45]
	v_cmp_lt_f32_e64 s[44:45], 0, v149
	s_nop 1
	v_cndmask_b32_e64 v145, v145, v147, s[44:45]
	v_mul_f32_e32 v146, 0x37800000, v145
	v_cndmask_b32_e32 v145, v145, v146, vcc
	v_cmp_class_f32_e32 vcc, v144, v213
	v_cmp_gt_i32_e64 s[44:45], s8, v170
	s_nop 0
	v_cndmask_b32_e32 v146, v145, v144, vcc
	v_div_scale_f32 v147, s[20:21], v146, v146, 1.0
	v_rcp_f32_e32 v148, v147
	v_lshlrev_b64 v[144:145], 11, v[192:193]
	v_lshl_add_u64 v[190:191], v[188:189], 0, v[144:145]
	v_fma_f32 v144, -v147, v148, 1.0
	v_fmac_f32_e32 v148, v144, v148
	v_div_scale_f32 v144, vcc, 1.0, v146, 1.0
	v_mul_f32_e32 v145, v144, v148
	v_fma_f32 v149, -v147, v145, v144
	v_fmac_f32_e32 v145, v149, v148
	v_fma_f32 v144, -v147, v145, v144
	v_div_fmas_f32 v144, v144, v148, v145
	v_div_fixup_f32 v148, v144, v146, 1.0
	v_pk_mul_f32 v[144:145], v[44:45], v[148:149] op_sel_hi:[1,0]
	v_pk_mul_f32 v[146:147], v[46:47], v[148:149] op_sel_hi:[1,0]
	v_pk_mul_f32 v[152:153], v[36:37], v[148:149] op_sel_hi:[1,0]
	v_pk_mul_f32 v[148:149], v[38:39], v[148:149] op_sel_hi:[1,0]
	v_pk_mul_f32 v[146:147], v[174:175], v[146:147]
	v_pk_mul_f32 v[144:145], v[176:177], v[144:145]
	v_pk_mul_f32 v[150:151], v[172:173], v[148:149]
	v_pk_mul_f32 v[148:149], v[178:179], v[152:153]
	s_and_b64 vcc, exec, s[42:43]
	v_cvt_pk_bf16_f32 v152, v144, v145
	v_cvt_pk_bf16_f32 v153, v146, v147
	v_cvt_pk_bf16_f32 v154, v148, v149
	v_cvt_pk_bf16_f32 v155, v150, v151
	s_cbranch_vccnz .LBB0_1050
	s_mov_b64 s[22:23], 0
	global_store_dwordx4 v[190:191], v[152:155], off nt
.LBB0_1050:
	v_readlane_b32 s8, v252, 35
	v_add_u32_e32 v182, 0xffff8060, v170
	v_cndmask_b32_e64 v183, 0, v193, s[0:1]
	v_mov_b32_e32 v184, s8
	v_readlane_b32 s8, v252, 33
	v_cndmask_b32_e64 v182, v182, v192, s[0:1]
	v_lshlrev_b64 v[182:183], 12, v[182:183]
	v_mov_b32_e32 v185, s8
	v_readlane_b32 s8, v252, 34
	v_cndmask_b32_e64 v185, v184, v185, s[0:1]
	v_ashrrev_i32_e32 v195, 31, v194
	v_mov_b32_e32 v184, s8
	v_readlane_b32 s8, v252, 32
	v_or_b32_e32 v171, v171, v199
	s_and_b64 s[20:21], s[40:41], s[44:45]
	v_mov_b32_e32 v192, s8
	v_cndmask_b32_e64 v184, v184, v192, s[0:1]
	v_lshl_add_u64 v[182:183], v[184:185], 0, v[182:183]
	v_lshl_add_u64 v[192:193], v[182:183], 0, v[180:181]
	v_lshlrev_b64 v[194:195], 16, v[194:195]
	s_andn2_b64 vcc, exec, s[22:23]
	v_lshlrev_b32_e32 v171, 3, v171
	s_cbranch_vccnz .LBB0_1054
	s_and_saveexec_b64 s[0:1], s[20:21]
	s_cbranch_execz .LBB0_1053
	v_readlane_b32 s22, v252, 16
	v_readlane_b32 s23, v252, 17
	s_lshl_b32 s8, s24, 1
	v_lshlrev_b32_e32 v184, 1, v171
	v_lshl_add_u64 v[182:183], s[22:23], 0, v[194:195]
	v_lshl_add_u64 v[182:183], v[182:183], 0, s[8:9]
	v_mov_b32_e32 v185, v181
	v_lshl_add_u64 v[182:183], v[182:183], 0, v[184:185]
	global_store_dwordx4 v[182:183], v[152:155], off nt
	global_store_dwordx4 v[192:193], v[144:147], off nt
	global_store_dwordx4 v[192:193], v[148:151], off offset:16 nt

; #define LAS __attribute__((address_space(3)))
; __device__ __forceinline__ u32x2 pk4(const f32x4 v) { u32x2 w; w.x = pk2(v[0], v[1]); w.y = pk2(v[2], v[3]); return w; }
;     __device__ __forceinline__ void operator()(const AccT& acc, const Unit& u, int wr, int wc, int fr, int fq) const {
;     ...
;                         const f32x4 t = *(const LAS f32x4*)(xs + ((((wr * 2 + ai) * 4 + m) * 2 + bj) * 16 + fr) * 4);
;                         const float rn = 1.0f / sqrtf(((t[0] + t[1]) + (t[2] + t[3])) * (1.f / HD) + EPS);
;                         const f32x4 v0 = acc[ai][bj][m][0] * rn * gv[0], v1 = acc[ai][bj][m][1] * rn * gv[1];
;                         const u32x2 p0 = pk4(v0), p1 = pk4(v1); const u32x4 pw = {p0.x, p0.y, p1.x, p1.y};
;                         if (!isk) *(u32x4*)(O + (size_t)row * DM + bj * 128) = pw;
.LBB0_1054:
	v_add_u32_e32 v144, s89, v201
	ds_read_b128 v[144:147], v144
	s_mov_b32 s0, 0xf800000
	s_waitcnt lgkmcnt(0)
	v_mov_b32_e32 v148, v145
	v_mov_b32_e32 v149, v146
	v_mov_b32_e32 v145, v147
	v_pk_add_f32 v[144:145], v[148:149], v[144:145]
	s_nop 0
	v_add_f32_e32 v144, v144, v145
	v_fmamk_f32 v144, v144, 0x3c000000, v212
	v_mul_f32_e32 v145, 0x4f800000, v144
	v_cmp_gt_f32_e32 vcc, s0, v144
	s_nop 1
	v_cndmask_b32_e32 v144, v144, v145, vcc
	v_sqrt_f32_e32 v145, v144
	s_nop 0
	v_add_u32_e32 v146, -1, v145
	v_add_u32_e32 v147, 1, v145
	v_fma_f32 v148, -v146, v145, v144
	v_fma_f32 v149, -v147, v145, v144
	v_cmp_ge_f32_e64 s[0:1], 0, v148
	s_nop 1
	v_cndmask_b32_e64 v145, v145, v146, s[0:1]
	v_cmp_lt_f32_e64 s[0:1], 0, v149
	s_nop 1
	v_cndmask_b32_e64 v145, v145, v147, s[0:1]
	v_mul_f32_e32 v146, 0x37800000, v145
	v_cndmask_b32_e32 v145, v145, v146, vcc
	v_cmp_class_f32_e32 vcc, v144, v213
	s_nop 1
	v_cndmask_b32_e32 v144, v145, v144, vcc
	v_div_scale_f32 v145, s[0:1], v144, v144, 1.0
	v_rcp_f32_e32 v146, v145
	s_mov_b64 s[0:1], -1
	v_fma_f32 v147, -v145, v146, 1.0
	v_fmac_f32_e32 v146, v147, v146
	v_div_scale_f32 v147, vcc, 1.0, v144, 1.0
	v_mul_f32_e32 v148, v147, v146
	v_fma_f32 v149, -v145, v148, v147
	v_fmac_f32_e32 v148, v149, v146
	v_fma_f32 v145, -v145, v148, v147
	v_div_fmas_f32 v145, v145, v146, v148
	v_div_fixup_f32 v148, v145, v144, 1.0
	v_pk_mul_f32 v[144:145], v[40:41], v[148:149] op_sel_hi:[1,0]
	v_pk_mul_f32 v[146:147], v[42:43], v[148:149] op_sel_hi:[1,0]
	v_pk_mul_f32 v[152:153], v[32:33], v[148:149] op_sel_hi:[1,0]
	v_pk_mul_f32 v[148:149], v[34:35], v[148:149] op_sel_hi:[1,0]
	v_pk_mul_f32 v[146:147], v[174:175], v[146:147]
	v_pk_mul_f32 v[144:145], v[176:177], v[144:145]
	v_pk_mul_f32 v[150:151], v[172:173], v[148:149]
	v_pk_mul_f32 v[148:149], v[178:179], v[152:153]
	s_and_b64 vcc, exec, s[42:43]
	v_cvt_pk_bf16_f32 v152, v144, v145
	v_cvt_pk_bf16_f32 v153, v146, v147
	v_cvt_pk_bf16_f32 v154, v148, v149
	v_cvt_pk_bf16_f32 v155, v150, v151
	s_cbranch_vccnz .LBB0_1056
	s_mov_b64 s[0:1], 0
	global_store_dwordx4 v[190:191], v[152:155], off offset:256 nt

; #define LAS __attribute__((address_space(3)))
; __device__ __forceinline__ size_t ksw_off(int sblk, int hd) { return ((size_t)sblk * NHEAD + hd) * 4096; }
; __device__ __forceinline__ u32x2 pk4(const f32x4 v) { u32x2 w; w.x = pk2(v[0], v[1]); w.y = pk2(v[2], v[3]); return w; }
;     __device__ __forceinline__ void operator()(const AccT& acc, const Unit& u, int wr, int wc, int fr, int fq) const {
;     ...
;                     const int row = row0 + ai * 128 + m * 16;
;                     float* ko = (row < MP ? kp + (size_t)row * DM : ks + (size_t)(row - MP) * DM) + colt;
;                     const bool kok = isk && row < MV;
;                     int sblk, kr;
;                     if (row < MP) { const int b = row / TP, t = row - b * TP; sblk = b * NGRP_ + (t >> 5); kr = t & 31; } else { const int q = row - MP; sblk = NBP * NGRP_ + (q >> 4); kr = q & 15; }
; #pragma unroll
;                     for (int bj = 0; bj < 2; ++bj) {
;                         const f32x4 t = *(const LAS f32x4*)(xs + ((((wr * 2 + ai) * 4 + m) * 2 + bj) * 16 + fr) * 4);
;                         const float rn = 1.0f / sqrtf(((t[0] + t[1]) + (t[2] + t[3])) * (1.f / HD) + EPS);
;                         const f32x4 v0 = acc[ai][bj][m][0] * rn * gv[0], v1 = acc[ai][bj][m][1] * rn * gv[1];
;                         const u32x2 p0 = pk4(v0), p1 = pk4(v1); const u32x4 pw = {p0.x, p0.y, p1.x, p1.y};
;                         if (!isk) *(u32x4*)(O + (size_t)row * DM + bj * 128) = pw;
;                         else if (kok) { *(u32x4*)(ksw + ksw_off(sblk, 2 * (pn & 3) + bj) + ((2 * wc + (fq >> 1)) * 64 + kr + 32 * (fq & 1)) * 8) = pw;
;                             __builtin_nontemporal_store(v0, (f32x4*)(ko + bj * 128)); __builtin_nontemporal_store(v1, (f32x4*)(ko + bj * 128 + 4)); }
.LBB0_1060:
	s_movk_i32 s0, 0x7f90
	s_movk_i32 s8, 0x7f8f
	v_cmp_gt_i32_e64 s[0:1], s0, v170
	v_cmp_lt_i32_e32 vcc, s8, v170
	s_and_saveexec_b64 s[20:21], vcc
	s_xor_b64 s[20:21], exec, s[20:21]
	s_addk_i32 s51, 0x8070
	s_lshr_b32 s8, s51, 4
	s_addk_i32 s8, 0x404
	s_or_saveexec_b64 s[20:21], s[20:21]
	v_add_u32_e32 v190, 0xb0, v170
	v_ashrrev_i32_e32 v191, 31, v190
	v_mov_b32_e32 v192, s8
	v_mov_b32_e32 v171, v196
	s_xor_b64 exec, exec, s[20:21]
	v_mul_hi_i32 v144, v190, s82
	v_lshrrev_b32_e32 v145, 31, v144
	v_ashrrev_i32_e32 v144, 12, v144
	v_add_u32_e32 v144, v144, v145
	v_mad_i32_i24 v145, v144, s83, v190
	v_ashrrev_i32_e32 v146, 5, v145
	s_movk_i32 s8, 0x101
	v_mad_i32_i24 v192, v144, s8, v146
	v_and_b32_e32 v171, 31, v145
	s_or_b64 exec, exec, s[20:21]
	v_add_u32_e32 v144, s91, v200
	ds_read_b128 v[144:147], v144
	s_mov_b32 s8, 0xf800000
	s_mov_b64 s[22:23], -1
	s_waitcnt lgkmcnt(0)
	v_mov_b32_e32 v148, v145
	v_mov_b32_e32 v149, v146
	v_mov_b32_e32 v145, v147
	v_pk_add_f32 v[144:145], v[148:149], v[144:145]
	s_nop 0
	v_add_f32_e32 v144, v144, v145
	v_fmamk_f32 v144, v144, 0x3c000000, v212
	v_mul_f32_e32 v145, 0x4f800000, v144
	v_cmp_gt_f32_e32 vcc, s8, v144
	s_mov_b32 s8, 0x8090
	s_nop 0
	v_cndmask_b32_e32 v144, v144, v145, vcc
	v_sqrt_f32_e32 v145, v144
	s_nop 0
	v_add_u32_e32 v146, -1, v145
	v_add_u32_e32 v147, 1, v145
	v_fma_f32 v148, -v146, v145, v144
	v_fma_f32 v149, -v147, v145, v144
	v_cmp_ge_f32_e64 s[44:45], 0, v148
	s_nop 1
	v_cndmask_b32_e64 v145, v145, v146, s[44:45]
	v_cmp_lt_f32_e64 s[44:45], 0, v149
	s_nop 1
	v_cndmask_b32_e64 v145, v145, v147, s[44:45]
	v_mul_f32_e32 v146, 0x37800000, v145
	v_cndmask_b32_e32 v145, v145, v146, vcc
	v_cmp_class_f32_e32 vcc, v144, v213
	v_cmp_gt_i32_e64 s[44:45], s8, v170
	s_nop 0
	v_cndmask_b32_e32 v146, v145, v144, vcc
	v_div_scale_f32 v147, s[20:21], v146, v146, 1.0
	v_rcp_f32_e32 v148, v147
	v_lshlrev_b64 v[144:145], 11, v[190:191]
	v_lshl_add_u64 v[188:189], v[188:189], 0, v[144:145]
	v_fma_f32 v144, -v147, v148, 1.0
	v_fmac_f32_e32 v148, v144, v148
	v_div_scale_f32 v144, vcc, 1.0, v146, 1.0
	v_mul_f32_e32 v145, v144, v148
	v_fma_f32 v149, -v147, v145, v144
	v_fmac_f32_e32 v145, v149, v148
	v_fma_f32 v144, -v147, v145, v144
	v_div_fmas_f32 v144, v144, v148, v145
	v_div_fixup_f32 v148, v144, v146, 1.0
	v_pk_mul_f32 v[144:145], v[28:29], v[148:149] op_sel_hi:[1,0]
	v_pk_mul_f32 v[146:147], v[30:31], v[148:149] op_sel_hi:[1,0]
	v_pk_mul_f32 v[152:153], v[20:21], v[148:149] op_sel_hi:[1,0]
	v_pk_mul_f32 v[148:149], v[22:23], v[148:149] op_sel_hi:[1,0]
	v_pk_mul_f32 v[146:147], v[174:175], v[146:147]
	v_pk_mul_f32 v[144:145], v[176:177], v[144:145]
	v_pk_mul_f32 v[150:151], v[172:173], v[148:149]
	v_pk_mul_f32 v[148:149], v[178:179], v[152:153]
	s_and_b64 vcc, exec, s[42:43]
	v_cvt_pk_bf16_f32 v152, v144, v145
	v_cvt_pk_bf16_f32 v153, v146, v147
	v_cvt_pk_bf16_f32 v154, v148, v149
	v_cvt_pk_bf16_f32 v155, v150, v151
	s_cbranch_vccnz .LBB0_1066
	s_mov_b64 s[22:23], 0
	global_store_dwordx4 v[188:189], v[152:155], off nt
.LBB0_1066:
	v_readlane_b32 s8, v252, 35
	v_add_u32_e32 v182, 0xffff8070, v170
	v_cndmask_b32_e64 v183, 0, v191, s[0:1]
	v_mov_b32_e32 v184, s8
	v_readlane_b32 s8, v252, 33
	v_cndmask_b32_e64 v182, v182, v190, s[0:1]
	v_lshlrev_b64 v[182:183], 12, v[182:183]
	v_mov_b32_e32 v185, s8
	v_readlane_b32 s8, v252, 34
	v_cndmask_b32_e64 v185, v184, v185, s[0:1]
	v_ashrrev_i32_e32 v193, 31, v192
	v_mov_b32_e32 v184, s8
	v_readlane_b32 s8, v252, 32
	v_or_b32_e32 v171, v171, v199
	s_and_b64 s[20:21], s[40:41], s[44:45]
	v_mov_b32_e32 v190, s8
	v_cndmask_b32_e64 v184, v184, v190, s[0:1]
	v_lshl_add_u64 v[182:183], v[184:185], 0, v[182:183]
	v_lshl_add_u64 v[190:191], v[182:183], 0, v[180:181]
	v_lshlrev_b64 v[192:193], 16, v[192:193]
	s_andn2_b64 vcc, exec, s[22:23]
	v_lshlrev_b32_e32 v171, 3, v171
	s_cbranch_vccnz .LBB0_1070
	s_and_saveexec_b64 s[0:1], s[20:21]
	s_cbranch_execz .LBB0_1069
	v_readlane_b32 s22, v252, 16
	v_readlane_b32 s23, v252, 17
	s_lshl_b32 s8, s24, 1
	v_lshlrev_b32_e32 v180, 1, v171
	v_lshl_add_u64 v[182:183], s[22:23], 0, v[192:193]
	v_lshl_add_u64 v[182:183], v[182:183], 0, s[8:9]
	v_lshl_add_u64 v[182:183], v[182:183], 0, v[180:181]
	global_store_dwordx4 v[182:183], v[152:155], off nt
	global_store_dwordx4 v[190:191], v[144:147], off nt
	global_store_dwordx4 v[190:191], v[148:151], off offset:16 nt

; #define LAS __attribute__((address_space(3)))
; __device__ __forceinline__ size_t ksw_off(int sblk, int hd) { return ((size_t)sblk * NHEAD + hd) * 4096; }
; __device__ __forceinline__ u32x2 pk4(const f32x4 v) { u32x2 w; w.x = pk2(v[0], v[1]); w.y = pk2(v[2], v[3]); return w; }
;     __device__ __forceinline__ void operator()(const AccT& acc, const Unit& u, int wr, int wc, int fr, int fq) const {
;     ...
;                         const f32x4 t = *(const LAS f32x4*)(xs + ((((wr * 2 + ai) * 4 + m) * 2 + bj) * 16 + fr) * 4);
;                         const float rn = 1.0f / sqrtf(((t[0] + t[1]) + (t[2] + t[3])) * (1.f / HD) + EPS);
;                         const f32x4 v0 = acc[ai][bj][m][0] * rn * gv[0], v1 = acc[ai][bj][m][1] * rn * gv[1];
;                         const u32x2 p0 = pk4(v0), p1 = pk4(v1); const u32x4 pw = {p0.x, p0.y, p1.x, p1.y};
;                         if (!isk) *(u32x4*)(O + (size_t)row * DM + bj * 128) = pw;
;                         else if (kok) { *(u32x4*)(ksw + ksw_off(sblk, 2 * (pn & 3) + bj) + ((2 * wc + (fq >> 1)) * 64 + kr + 32 * (fq & 1)) * 8) = pw;
;                             __builtin_nontemporal_store(v0, (f32x4*)(ko + bj * 128)); __builtin_nontemporal_store(v1, (f32x4*)(ko + bj * 128 + 4)); }
.LBB0_1070:
	v_add_u32_e32 v144, s91, v201
	ds_read_b128 v[144:147], v144
	s_mov_b32 s0, 0xf800000
	s_waitcnt lgkmcnt(0)
	v_mov_b32_e32 v148, v145
	v_mov_b32_e32 v149, v146
	v_mov_b32_e32 v145, v147
	v_pk_add_f32 v[144:145], v[148:149], v[144:145]
	s_nop 0
	v_add_f32_e32 v144, v144, v145
	v_fmamk_f32 v144, v144, 0x3c000000, v212
	v_mul_f32_e32 v145, 0x4f800000, v144
	v_cmp_gt_f32_e32 vcc, s0, v144
	s_nop 1
	v_cndmask_b32_e32 v144, v144, v145, vcc
	v_sqrt_f32_e32 v145, v144
	s_nop 0
	v_add_u32_e32 v146, -1, v145
	v_add_u32_e32 v147, 1, v145
	v_fma_f32 v148, -v146, v145, v144
	v_fma_f32 v149, -v147, v145, v144
	v_cmp_ge_f32_e64 s[0:1], 0, v148
	s_nop 1
	v_cndmask_b32_e64 v145, v145, v146, s[0:1]
	v_cmp_lt_f32_e64 s[0:1], 0, v149
	s_nop 1
	v_cndmask_b32_e64 v145, v145, v147, s[0:1]
	v_mul_f32_e32 v146, 0x37800000, v145
	v_cndmask_b32_e32 v145, v145, v146, vcc
	v_cmp_class_f32_e32 vcc, v144, v213
	s_nop 1
	v_cndmask_b32_e32 v144, v145, v144, vcc
	v_div_scale_f32 v145, s[0:1], v144, v144, 1.0
	v_rcp_f32_e32 v146, v145
	s_mov_b64 s[0:1], -1
	v_fma_f32 v147, -v145, v146, 1.0
	v_fmac_f32_e32 v146, v147, v146
	v_div_scale_f32 v147, vcc, 1.0, v144, 1.0
	v_mul_f32_e32 v148, v147, v146
	v_fma_f32 v149, -v145, v148, v147
	v_fmac_f32_e32 v148, v149, v146
	v_fma_f32 v145, -v145, v148, v147
	v_div_fmas_f32 v145, v145, v146, v148
	v_div_fixup_f32 v148, v145, v144, 1.0
	v_pk_mul_f32 v[144:145], v[24:25], v[148:149] op_sel_hi:[1,0]
	v_pk_mul_f32 v[146:147], v[26:27], v[148:149] op_sel_hi:[1,0]
	v_pk_mul_f32 v[152:153], v[16:17], v[148:149] op_sel_hi:[1,0]
	v_pk_mul_f32 v[148:149], v[18:19], v[148:149] op_sel_hi:[1,0]
	v_pk_mul_f32 v[146:147], v[174:175], v[146:147]
	v_pk_mul_f32 v[144:145], v[176:177], v[144:145]
	v_pk_mul_f32 v[150:151], v[172:173], v[148:149]
	v_pk_mul_f32 v[148:149], v[178:179], v[152:153]
	s_and_b64 vcc, exec, s[42:43]
	v_cvt_pk_bf16_f32 v152, v144, v145
	v_cvt_pk_bf16_f32 v153, v146, v147
	v_cvt_pk_bf16_f32 v154, v148, v149
	v_cvt_pk_bf16_f32 v155, v150, v151
	s_cbranch_vccnz .LBB0_1072
	s_mov_b64 s[0:1], 0
	global_store_dwordx4 v[188:189], v[152:155], off offset:256 nt
.LBB0_1072:
	s_andn2_b64 vcc, exec, s[0:1]
	s_cbranch_vccnz .LBB0_1076
	s_and_saveexec_b64 s[0:1], s[20:21]
	s_cbranch_execz .LBB0_1075
	v_readlane_b32 s20, v252, 16
	v_readlane_b32 s21, v252, 17
	s_lshl_b32 s8, s24, 1
	v_lshlrev_b32_e32 v180, 1, v171
	v_lshl_add_u64 v[172:173], s[20:21], 0, v[192:193]
	v_lshl_add_u64 v[172:173], v[172:173], 0, s[8:9]
	v_lshl_add_u64 v[172:173], v[172:173], 0, v[180:181]
	v_add_co_u32_e32 v172, vcc, 0x2000, v172
	s_nop 1
	v_addc_co_u32_e32 v173, vcc, 0, v173, vcc
	global_store_dwordx4 v[172:173], v[152:155], off nt
	global_store_dwordx4 v[190:191], v[144:147], off offset:512 nt
	global_store_dwordx4 v[190:191], v[148:151], off offset:528 nt
